# plus: nt hint on the single-use gate / residual / G1 loads of the branch and output projection epilogues
# speedup vs baseline: 1.0146x; 1.0146x over previous
; #define GAS __attribute__((address_space(1)))
; __device__ __forceinline__ float bflo(unsigned w) { return __uint_as_float(w << 16); }
; __device__ __forceinline__ float bfhi(unsigned w) { return __uint_as_float(w & 0xffff0000u); }
; __device__ __forceinline__ f32x4 bperm_f4(int src4, f32x4 v) { return (f32x4){bperm_f(src4, v.x), bperm_f(src4, v.y), bperm_f(src4, v.z), bperm_f(src4, v.w)}; }
;     __device__ __forceinline__ void operator()(const pg8::f32x4 (&acc)[2][2][4][2], const pg8::Unit& u, int wr, int wc, int fr, int fq) const {
;     ...
;             for (int ai = 0; ai < 2; ++ai) {
;                 u32x4 gt[4][2];
; #pragma unroll
;                 for (int m = 0; m < 4; ++m)
; #pragma unroll
;                     for (int bj = 0; bj < 2; ++bj) gt[m][bj] = *(const GAS u32x4*)(P + (size_t)(row0 + ai * 128 + m * 16) * NP + gcol + col0 + bj * 128);
;                 __builtin_amdgcn_sched_barrier(0);
; #pragma unroll
;                 for (int m = 0; m < 4; ++m)
; #pragma unroll
;                     for (int bj = 0; bj < 2; ++bj) {
;                         const u32x4 g = gt[m][bj]; const f32x4 a0 = bperm_f4(src4, acc[ai][bj][m][0]), a1 = bperm_f4(src4, acc[ai][bj][m][1]);
;                         float* gp = G1 + (size_t)(row0 + ai * 128 + m * 16) * DM + col0 + bj * 128;
;                         *(GAS f32x4*)gp = (f32x4){a0.x * bflo(g.x), a0.y * bfhi(g.x), a0.z * bflo(g.y), a0.w * bfhi(g.y)};
;                         *(GAS f32x4*)(gp + 4) = (f32x4){a1.x * bflo(g.z), a1.y * bfhi(g.z), a1.z * bflo(g.w), a1.w * bfhi(g.w)};
;                     }
;                 __builtin_amdgcn_sched_barrier(0);
;             }
.LBB0_1116:
	s_lshl_b32 s13, s42, 8
	s_and_b32 s13, s13, 0x1f00
	s_lshl_b32 s15, s41, 8
	v_add_u32_e32 v170, s13, v180
	s_and_b32 s15, s15, 0x700
	v_ashrrev_i32_e32 v171, 31, v170
	v_or_b32_e32 v132, s15, v181
	v_mad_i64_i32 v[172:173], s[22:23], v170, s74, 0
	v_lshlrev_b64 v[130:131], 13, v[170:171]
	s_cmp_gt_i32 s42, 31
	s_mov_b64 s[22:23], -1
	v_lshlrev_b32_e32 v0, 1, v132
	v_or_b32_e32 v168, 16, v170
	v_or_b32_e32 v166, 32, v170
	v_or_b32_e32 v164, 48, v170
	v_lshl_add_u64 v[174:175], s[2:3], 0, v[130:131]
	v_lshlrev_b32_e32 v158, 2, v132
	v_add_u32_e32 v162, 0x80, v170
	v_add_u32_e32 v160, 0x90, v170
	v_add_u32_e32 v156, 0xa0, v170
	v_add_u32_e32 v154, 0xb0, v170
	s_cbranch_scc1 .LBB0_1119
	v_lshl_add_u64 v[176:177], s[6:7], 0, v[0:1]
	v_lshl_add_u64 v[130:131], v[176:177], 0, v[172:173]
	global_load_dwordx4 v[190:193], v[130:131], off nt
	global_load_dwordx4 v[194:197], v[130:131], off offset:256 nt
	v_mad_i64_i32 v[130:131], s[22:23], v168, s74, v[176:177]
	global_load_dwordx4 v[198:201], v[130:131], off nt
	global_load_dwordx4 v[202:205], v[130:131], off offset:256 nt
	v_mad_i64_i32 v[130:131], s[22:23], v166, s74, v[176:177]
	global_load_dwordx4 v[206:209], v[130:131], off nt
	global_load_dwordx4 v[138:141], v[130:131], off offset:256 nt
	v_mad_i64_i32 v[130:131], s[22:23], v164, s74, v[176:177]
	global_load_dwordx4 v[134:137], v[130:131], off nt
	s_nop 0
	global_load_dwordx4 v[130:133], v[130:131], off offset:256 nt
	v_ashrrev_i32_e32 v169, 31, v168
	v_ashrrev_i32_e32 v167, 31, v166
	v_ashrrev_i32_e32 v165, 31, v164
	ds_bpermute_b32 v184, v179, v126
	ds_bpermute_b32 v185, v179, v127
	ds_bpermute_b32 v212, v179, v128
	ds_bpermute_b32 v213, v179, v129
	ds_bpermute_b32 v214, v179, v122
	ds_bpermute_b32 v215, v179, v123
	ds_bpermute_b32 v216, v179, v124
	ds_bpermute_b32 v217, v179, v125
	s_waitcnt vmcnt(0)
	v_lshlrev_b32_e32 v210, 16, v190
	v_and_b32_e32 v211, 0xffff0000, v190
	s_waitcnt lgkmcnt(6)
	v_pk_mul_f32 v[210:211], v[210:211], v[184:185]
	v_lshlrev_b32_e32 v184, 16, v191
	v_and_b32_e32 v185, 0xffff0000, v191
	s_waitcnt lgkmcnt(4)
	v_pk_mul_f32 v[212:213], v[184:185], v[212:213]
	v_lshlrev_b32_e32 v184, 16, v192
	v_and_b32_e32 v185, 0xffff0000, v192
	v_mov_b32_e32 v159, v1
	s_waitcnt lgkmcnt(2)
	v_pk_mul_f32 v[190:191], v[184:185], v[214:215]
	v_lshlrev_b32_e32 v184, 16, v193
	v_and_b32_e32 v185, 0xffff0000, v193
	v_lshl_add_u64 v[218:219], v[174:175], 0, v[158:159]
	s_waitcnt lgkmcnt(0)
	v_pk_mul_f32 v[192:193], v[184:185], v[216:217]
	ds_bpermute_b32 v184, v179, v118
	ds_bpermute_b32 v185, v179, v119
	global_store_dwordx4 v[218:219], v[190:193], off offset:16
	ds_bpermute_b32 v192, v179, v120
	ds_bpermute_b32 v193, v179, v121
	global_store_dwordx4 v[218:219], v[210:213], off
	ds_bpermute_b32 v210, v179, v114
	ds_bpermute_b32 v211, v179, v115
	ds_bpermute_b32 v212, v179, v116
	ds_bpermute_b32 v213, v179, v117
	v_lshlrev_b32_e32 v190, 16, v194
	v_and_b32_e32 v191, 0xffff0000, v194
	s_waitcnt lgkmcnt(6)
	v_pk_mul_f32 v[190:191], v[190:191], v[184:185]
	v_lshlrev_b32_e32 v184, 16, v195
	v_and_b32_e32 v185, 0xffff0000, v195
	s_waitcnt lgkmcnt(4)
	v_pk_mul_f32 v[192:193], v[184:185], v[192:193]
	v_lshlrev_b32_e32 v184, 16, v196
	v_and_b32_e32 v185, 0xffff0000, v196
	global_store_dwordx4 v[218:219], v[190:193], off offset:512
	ds_bpermute_b32 v194, v179, v106
	ds_bpermute_b32 v195, v179, v107
	s_waitcnt lgkmcnt(4)
	v_pk_mul_f32 v[190:191], v[184:185], v[210:211]
	v_lshlrev_b32_e32 v184, 16, v197
	v_and_b32_e32 v185, 0xffff0000, v197
	s_waitcnt lgkmcnt(2)
	v_pk_mul_f32 v[192:193], v[184:185], v[212:213]
	global_store_dwordx4 v[218:219], v[190:193], off offset:528
	ds_bpermute_b32 v190, v179, v110
	ds_bpermute_b32 v191, v179, v111
	ds_bpermute_b32 v192, v179, v112
	ds_bpermute_b32 v193, v179, v113
	ds_bpermute_b32 v196, v179, v108
	ds_bpermute_b32 v197, v179, v109
	v_lshlrev_b64 v[184:185], 13, v[168:169]
	v_lshl_add_u64 v[184:185], s[2:3], 0, v[184:185]
	v_lshlrev_b32_e32 v210, 16, v198
	v_and_b32_e32 v211, 0xffff0000, v198
	v_lshlrev_b32_e32 v198, 16, v199
	v_and_b32_e32 v199, 0xffff0000, v199
	v_lshl_add_u64 v[184:185], v[184:185], 0, v[158:159]
	s_waitcnt lgkmcnt(4)
	v_pk_mul_f32 v[190:191], v[210:211], v[190:191]
	s_waitcnt lgkmcnt(2)
	v_pk_mul_f32 v[192:193], v[198:199], v[192:193]
	global_store_dwordx4 v[184:185], v[190:193], off
	v_lshlrev_b32_e32 v198, 16, v202
	v_and_b32_e32 v199, 0xffff0000, v202
	v_lshlrev_b32_e32 v190, 16, v200
	v_and_b32_e32 v191, 0xffff0000, v200
	v_lshlrev_b32_e32 v192, 16, v201
	v_and_b32_e32 v193, 0xffff0000, v201
	v_pk_mul_f32 v[190:191], v[190:191], v[194:195]
	s_waitcnt lgkmcnt(0)
	v_pk_mul_f32 v[192:193], v[192:193], v[196:197]
	global_store_dwordx4 v[184:185], v[190:193], off offset:16
	ds_bpermute_b32 v190, v179, v102
	ds_bpermute_b32 v191, v179, v103
	ds_bpermute_b32 v192, v179, v104
	ds_bpermute_b32 v193, v179, v105
	ds_bpermute_b32 v194, v179, v98
	ds_bpermute_b32 v195, v179, v99
	ds_bpermute_b32 v196, v179, v100
	ds_bpermute_b32 v197, v179, v101
	s_waitcnt lgkmcnt(6)
	v_pk_mul_f32 v[190:191], v[198:199], v[190:191]
	v_lshlrev_b32_e32 v198, 16, v203
	v_and_b32_e32 v199, 0xffff0000, v203
	s_waitcnt lgkmcnt(4)
	v_pk_mul_f32 v[192:193], v[198:199], v[192:193]
	global_store_dwordx4 v[184:185], v[190:193], off offset:512
	v_lshlrev_b32_e32 v198, 16, v206
	v_and_b32_e32 v199, 0xffff0000, v206
	v_lshlrev_b32_e32 v190, 16, v204
	v_and_b32_e32 v191, 0xffff0000, v204
	v_lshlrev_b32_e32 v192, 16, v205
	v_and_b32_e32 v193, 0xffff0000, v205
	s_waitcnt lgkmcnt(2)
	v_pk_mul_f32 v[190:191], v[190:191], v[194:195]
	s_waitcnt lgkmcnt(0)
; #define GAS __attribute__((address_space(1)))
; __device__ __forceinline__ float bflo(unsigned w) { return __uint_as_float(w << 16); }
; __device__ __forceinline__ float bfhi(unsigned w) { return __uint_as_float(w & 0xffff0000u); }
; __device__ __forceinline__ f32x4 bperm_f4(int src4, f32x4 v) { return (f32x4){bperm_f(src4, v.x), bperm_f(src4, v.y), bperm_f(src4, v.z), bperm_f(src4, v.w)}; }
;     __device__ __forceinline__ void operator()(const pg8::f32x4 (&acc)[2][2][4][2], const pg8::Unit& u, int wr, int wc, int fr, int fq) const {
;     ...
;             for (int ai = 0; ai < 2; ++ai) {
;                 u32x4 gt[4][2];
; #pragma unroll
;                 for (int m = 0; m < 4; ++m)
; #pragma unroll
;                     for (int bj = 0; bj < 2; ++bj) gt[m][bj] = *(const GAS u32x4*)(P + (size_t)(row0 + ai * 128 + m * 16) * NP + gcol + col0 + bj * 128);
;                 __builtin_amdgcn_sched_barrier(0);
; #pragma unroll
;                 for (int m = 0; m < 4; ++m)
; #pragma unroll
;                     for (int bj = 0; bj < 2; ++bj) {
;                         const u32x4 g = gt[m][bj]; const f32x4 a0 = bperm_f4(src4, acc[ai][bj][m][0]), a1 = bperm_f4(src4, acc[ai][bj][m][1]);
;                         float* gp = G1 + (size_t)(row0 + ai * 128 + m * 16) * DM + col0 + bj * 128;
;                         *(GAS f32x4*)gp = (f32x4){a0.x * bflo(g.x), a0.y * bfhi(g.x), a0.z * bflo(g.y), a0.w * bfhi(g.y)};
;                         *(GAS f32x4*)(gp + 4) = (f32x4){a1.x * bflo(g.z), a1.y * bfhi(g.z), a1.z * bflo(g.w), a1.w * bfhi(g.w)};
;                     }
;                 __builtin_amdgcn_sched_barrier(0);
;             }
	v_pk_mul_f32 v[192:193], v[192:193], v[196:197]
	global_store_dwordx4 v[184:185], v[190:193], off offset:528
	ds_bpermute_b32 v190, v179, v94
	ds_bpermute_b32 v191, v179, v95
	ds_bpermute_b32 v192, v179, v96
	ds_bpermute_b32 v193, v179, v97
	ds_bpermute_b32 v194, v179, v90
	ds_bpermute_b32 v195, v179, v91
	ds_bpermute_b32 v196, v179, v92
	ds_bpermute_b32 v197, v179, v93
	v_lshlrev_b64 v[184:185], 13, v[166:167]
	v_lshl_add_u64 v[184:185], s[2:3], 0, v[184:185]
	s_waitcnt lgkmcnt(6)
	v_pk_mul_f32 v[190:191], v[198:199], v[190:191]
	v_lshlrev_b32_e32 v198, 16, v207
	v_and_b32_e32 v199, 0xffff0000, v207
	v_lshl_add_u64 v[184:185], v[184:185], 0, v[158:159]
	s_waitcnt lgkmcnt(4)
	v_pk_mul_f32 v[192:193], v[198:199], v[192:193]
	global_store_dwordx4 v[184:185], v[190:193], off
	v_lshlrev_b32_e32 v198, 16, v138
	v_and_b32_e32 v199, 0xffff0000, v138
	v_lshlrev_b32_e32 v190, 16, v208
	v_and_b32_e32 v191, 0xffff0000, v208
	v_lshlrev_b32_e32 v192, 16, v209
	v_and_b32_e32 v193, 0xffff0000, v209
	s_waitcnt lgkmcnt(2)
	v_pk_mul_f32 v[190:191], v[190:191], v[194:195]
	s_waitcnt lgkmcnt(0)
	v_pk_mul_f32 v[192:193], v[192:193], v[196:197]
	global_store_dwordx4 v[184:185], v[190:193], off offset:16
	ds_bpermute_b32 v192, v179, v88
	ds_bpermute_b32 v193, v179, v89
	ds_bpermute_b32 v190, v179, v86
	ds_bpermute_b32 v191, v179, v87
	ds_bpermute_b32 v194, v179, v82
	ds_bpermute_b32 v195, v179, v83
	ds_bpermute_b32 v196, v179, v84
	ds_bpermute_b32 v197, v179, v85
	v_lshlrev_b32_e32 v138, 16, v139
	v_and_b32_e32 v139, 0xffff0000, v139
	s_waitcnt lgkmcnt(6)
	v_pk_mul_f32 v[192:193], v[138:139], v[192:193]
	v_lshlrev_b32_e32 v138, 16, v140
	v_and_b32_e32 v139, 0xffff0000, v140
	v_lshlrev_b32_e32 v140, 16, v141
	v_and_b32_e32 v141, 0xffff0000, v141
	s_waitcnt lgkmcnt(4)
	v_pk_mul_f32 v[190:191], v[198:199], v[190:191]
	s_waitcnt lgkmcnt(2)
	v_pk_mul_f32 v[138:139], v[138:139], v[194:195]
	s_waitcnt lgkmcnt(0)
	v_pk_mul_f32 v[140:141], v[140:141], v[196:197]
	global_store_dwordx4 v[184:185], v[190:193], off offset:512
	global_store_dwordx4 v[184:185], v[138:141], off offset:528
	ds_bpermute_b32 v140, v179, v78
	ds_bpermute_b32 v141, v179, v79
	ds_bpermute_b32 v184, v179, v80
	ds_bpermute_b32 v185, v179, v81
	ds_bpermute_b32 v190, v179, v74
	ds_bpermute_b32 v191, v179, v75
	ds_bpermute_b32 v192, v179, v76
	ds_bpermute_b32 v193, v179, v77
	v_lshlrev_b64 v[138:139], 13, v[164:165]
	v_lshl_add_u64 v[138:139], s[2:3], 0, v[138:139]
	v_lshl_add_u64 v[194:195], v[138:139], 0, v[158:159]
	v_lshlrev_b32_e32 v138, 16, v134
	v_and_b32_e32 v139, 0xffff0000, v134
	v_lshlrev_b32_e32 v134, 16, v135
	v_and_b32_e32 v135, 0xffff0000, v135
	s_waitcnt lgkmcnt(6)
	v_pk_mul_f32 v[138:139], v[138:139], v[140:141]
	s_waitcnt lgkmcnt(4)
	v_pk_mul_f32 v[140:141], v[134:135], v[184:185]
	v_lshlrev_b32_e32 v134, 16, v136
	v_and_b32_e32 v135, 0xffff0000, v136
	v_lshlrev_b32_e32 v136, 16, v137
	v_and_b32_e32 v137, 0xffff0000, v137
	s_waitcnt lgkmcnt(2)
	v_pk_mul_f32 v[134:135], v[134:135], v[190:191]
	s_waitcnt lgkmcnt(0)
	v_pk_mul_f32 v[136:137], v[136:137], v[192:193]
	global_store_dwordx4 v[194:195], v[134:137], off offset:16
	ds_bpermute_b32 v136, v179, v72
	ds_bpermute_b32 v137, v179, v73
	global_store_dwordx4 v[194:195], v[138:141], off
	ds_bpermute_b32 v134, v179, v70
	ds_bpermute_b32 v135, v179, v71
	ds_bpermute_b32 v138, v179, v66
	ds_bpermute_b32 v139, v179, v67
	ds_bpermute_b32 v140, v179, v68
	ds_bpermute_b32 v141, v179, v69
	v_lshlrev_b32_e32 v184, 16, v130
	v_and_b32_e32 v185, 0xffff0000, v130
	v_lshlrev_b32_e32 v130, 16, v131
	v_and_b32_e32 v131, 0xffff0000, v131
	s_waitcnt lgkmcnt(6)
	v_pk_mul_f32 v[136:137], v[130:131], v[136:137]
	v_lshlrev_b32_e32 v130, 16, v132
	v_and_b32_e32 v131, 0xffff0000, v132
	v_lshlrev_b32_e32 v132, 16, v133
	v_and_b32_e32 v133, 0xffff0000, v133
	s_waitcnt lgkmcnt(4)
	v_pk_mul_f32 v[134:135], v[184:185], v[134:135]
	s_waitcnt lgkmcnt(2)
	v_pk_mul_f32 v[130:131], v[130:131], v[138:139]
	s_waitcnt lgkmcnt(0)
	v_pk_mul_f32 v[132:133], v[132:133], v[140:141]
	global_store_dwordx4 v[194:195], v[134:137], off offset:512
	global_store_dwordx4 v[194:195], v[130:133], off offset:528
	s_nop 1
	v_mad_i64_i32 v[130:131], s[22:23], v162, s74, v[176:177]
	global_load_dwordx4 v[190:193], v[130:131], off nt
	global_load_dwordx4 v[194:197], v[130:131], off offset:256 nt
	v_mad_i64_i32 v[130:131], s[22:23], v160, s74, v[176:177]
	global_load_dwordx4 v[198:201], v[130:131], off nt
	global_load_dwordx4 v[202:205], v[130:131], off offset:256 nt
	v_mad_i64_i32 v[130:131], s[22:23], v156, s74, v[176:177]
	global_load_dwordx4 v[206:209], v[130:131], off nt
	global_load_dwordx4 v[138:141], v[130:131], off offset:256 nt
	v_mad_i64_i32 v[130:131], s[22:23], v154, s74, v[176:177]
	global_load_dwordx4 v[134:137], v[130:131], off nt
	s_nop 0
	global_load_dwordx4 v[130:133], v[130:131], off offset:256 nt
	v_ashrrev_i32_e32 v163, 31, v162
	v_ashrrev_i32_e32 v161, 31, v160
	v_ashrrev_i32_e32 v157, 31, v156
	v_ashrrev_i32_e32 v155, 31, v154
	ds_bpermute_b32 v184, v179, v62
	ds_bpermute_b32 v185, v179, v63
	ds_bpermute_b32 v212, v179, v64
	ds_bpermute_b32 v213, v179, v65
	ds_bpermute_b32 v214, v179, v58
	ds_bpermute_b32 v215, v179, v59
	ds_bpermute_b32 v216, v179, v60
	ds_bpermute_b32 v217, v179, v61
	s_waitcnt vmcnt(7)
	v_lshlrev_b32_e32 v210, 16, v190
	v_and_b32_e32 v211, 0xffff0000, v190
	s_waitcnt lgkmcnt(6)
	v_pk_mul_f32 v[210:211], v[210:211], v[184:185]
	v_lshlrev_b32_e32 v184, 16, v191
	v_and_b32_e32 v185, 0xffff0000, v191
	v_lshlrev_b64 v[176:177], 13, v[162:163]
	s_waitcnt lgkmcnt(4)
; #define GAS __attribute__((address_space(1)))
; __device__ __forceinline__ float bflo(unsigned w) { return __uint_as_float(w << 16); }
; __device__ __forceinline__ float bfhi(unsigned w) { return __uint_as_float(w & 0xffff0000u); }
; __device__ __forceinline__ f32x4 bperm_f4(int src4, f32x4 v) { return (f32x4){bperm_f(src4, v.x), bperm_f(src4, v.y), bperm_f(src4, v.z), bperm_f(src4, v.w)}; }
;     __device__ __forceinline__ void operator()(const pg8::f32x4 (&acc)[2][2][4][2], const pg8::Unit& u, int wr, int wc, int fr, int fq) const {
;     ...
;                     for (int bj = 0; bj < 2; ++bj) gt[m][bj] = *(const GAS u32x4*)(P + (size_t)(row0 + ai * 128 + m * 16) * NP + gcol + col0 + bj * 128);
;                 __builtin_amdgcn_sched_barrier(0);
; #pragma unroll
;                 for (int m = 0; m < 4; ++m)
; #pragma unroll
;                     for (int bj = 0; bj < 2; ++bj) {
;                         const u32x4 g = gt[m][bj]; const f32x4 a0 = bperm_f4(src4, acc[ai][bj][m][0]), a1 = bperm_f4(src4, acc[ai][bj][m][1]);
;                         float* gp = G1 + (size_t)(row0 + ai * 128 + m * 16) * DM + col0 + bj * 128;
;                         *(GAS f32x4*)gp = (f32x4){a0.x * bflo(g.x), a0.y * bfhi(g.x), a0.z * bflo(g.y), a0.w * bfhi(g.y)};
;                         *(GAS f32x4*)(gp + 4) = (f32x4){a1.x * bflo(g.z), a1.y * bfhi(g.z), a1.z * bflo(g.w), a1.w * bfhi(g.w)};
;                     }
;                 __builtin_amdgcn_sched_barrier(0);
;             }
	v_pk_mul_f32 v[212:213], v[184:185], v[212:213]
	v_lshlrev_b32_e32 v184, 16, v192
	v_and_b32_e32 v185, 0xffff0000, v192
	v_lshl_add_u64 v[176:177], s[2:3], 0, v[176:177]
	s_waitcnt lgkmcnt(2)
	v_pk_mul_f32 v[190:191], v[184:185], v[214:215]
	v_lshlrev_b32_e32 v184, 16, v193
	v_and_b32_e32 v185, 0xffff0000, v193
	v_lshl_add_u64 v[176:177], v[176:177], 0, v[158:159]
	s_waitcnt lgkmcnt(0)
	v_pk_mul_f32 v[192:193], v[184:185], v[216:217]
	ds_bpermute_b32 v184, v179, v54
	ds_bpermute_b32 v185, v179, v55
	global_store_dwordx4 v[176:177], v[190:193], off offset:16
	ds_bpermute_b32 v192, v179, v56
	ds_bpermute_b32 v193, v179, v57
	global_store_dwordx4 v[176:177], v[210:213], off
	ds_bpermute_b32 v210, v179, v50
	ds_bpermute_b32 v211, v179, v51
	ds_bpermute_b32 v212, v179, v52
	ds_bpermute_b32 v213, v179, v53
	s_waitcnt vmcnt(8)
	v_lshlrev_b32_e32 v190, 16, v194
	v_and_b32_e32 v191, 0xffff0000, v194
	s_waitcnt lgkmcnt(6)
	v_pk_mul_f32 v[190:191], v[190:191], v[184:185]
	v_lshlrev_b32_e32 v184, 16, v195
	v_and_b32_e32 v185, 0xffff0000, v195
	s_waitcnt lgkmcnt(4)
	v_pk_mul_f32 v[192:193], v[184:185], v[192:193]
	v_lshlrev_b32_e32 v184, 16, v196
	v_and_b32_e32 v185, 0xffff0000, v196
	global_store_dwordx4 v[176:177], v[190:193], off offset:512
	ds_bpermute_b32 v194, v179, v42
	ds_bpermute_b32 v195, v179, v43
	s_waitcnt lgkmcnt(4)
	v_pk_mul_f32 v[190:191], v[184:185], v[210:211]
	v_lshlrev_b32_e32 v184, 16, v197
	v_and_b32_e32 v185, 0xffff0000, v197
	s_waitcnt lgkmcnt(2)
	v_pk_mul_f32 v[192:193], v[184:185], v[212:213]
	ds_bpermute_b32 v184, v179, v46
	ds_bpermute_b32 v185, v179, v47
	global_store_dwordx4 v[176:177], v[190:193], off offset:528
	ds_bpermute_b32 v192, v179, v48
	ds_bpermute_b32 v193, v179, v49
	ds_bpermute_b32 v196, v179, v44
	ds_bpermute_b32 v197, v179, v45
	v_lshlrev_b64 v[176:177], 13, v[160:161]
	s_waitcnt vmcnt(9)
	v_lshlrev_b32_e32 v190, 16, v198
	v_and_b32_e32 v191, 0xffff0000, v198
	v_lshl_add_u64 v[176:177], s[2:3], 0, v[176:177]
	s_waitcnt lgkmcnt(4)
	v_pk_mul_f32 v[190:191], v[190:191], v[184:185]
	v_lshlrev_b32_e32 v184, 16, v199
	v_and_b32_e32 v185, 0xffff0000, v199
	v_lshl_add_u64 v[176:177], v[176:177], 0, v[158:159]
	s_waitcnt lgkmcnt(2)
	v_pk_mul_f32 v[192:193], v[184:185], v[192:193]
	v_lshlrev_b32_e32 v184, 16, v200
	v_and_b32_e32 v185, 0xffff0000, v200
	global_store_dwordx4 v[176:177], v[190:193], off
	s_nop 1
	v_pk_mul_f32 v[190:191], v[184:185], v[194:195]
	v_lshlrev_b32_e32 v184, 16, v201
	v_and_b32_e32 v185, 0xffff0000, v201
	s_waitcnt lgkmcnt(0)
	v_pk_mul_f32 v[192:193], v[184:185], v[196:197]
	ds_bpermute_b32 v184, v179, v38
	ds_bpermute_b32 v185, v179, v39
	global_store_dwordx4 v[176:177], v[190:193], off offset:16
	ds_bpermute_b32 v192, v179, v40
	ds_bpermute_b32 v193, v179, v41
	ds_bpermute_b32 v194, v179, v34
	ds_bpermute_b32 v195, v179, v35
	ds_bpermute_b32 v196, v179, v36
	ds_bpermute_b32 v197, v179, v37
	s_waitcnt vmcnt(10)
	v_lshlrev_b32_e32 v190, 16, v202
	v_and_b32_e32 v191, 0xffff0000, v202
	s_waitcnt lgkmcnt(6)
	v_pk_mul_f32 v[190:191], v[190:191], v[184:185]
	v_lshlrev_b32_e32 v184, 16, v203
	v_and_b32_e32 v185, 0xffff0000, v203
	s_waitcnt lgkmcnt(4)
	v_pk_mul_f32 v[192:193], v[184:185], v[192:193]
	v_lshlrev_b32_e32 v184, 16, v204
	v_and_b32_e32 v185, 0xffff0000, v204
	global_store_dwordx4 v[176:177], v[190:193], off offset:512
	s_waitcnt lgkmcnt(2)
	s_nop 0
	v_pk_mul_f32 v[190:191], v[184:185], v[194:195]
	v_lshlrev_b32_e32 v184, 16, v205
	v_and_b32_e32 v185, 0xffff0000, v205
	s_waitcnt lgkmcnt(0)
	v_pk_mul_f32 v[192:193], v[184:185], v[196:197]
	ds_bpermute_b32 v184, v179, v30
	ds_bpermute_b32 v185, v179, v31
	global_store_dwordx4 v[176:177], v[190:193], off offset:528
	ds_bpermute_b32 v192, v179, v32
	ds_bpermute_b32 v193, v179, v33
	ds_bpermute_b32 v194, v179, v26
	ds_bpermute_b32 v195, v179, v27
	ds_bpermute_b32 v196, v179, v28
	ds_bpermute_b32 v197, v179, v29
	v_lshlrev_b64 v[176:177], 13, v[156:157]
	s_waitcnt vmcnt(11)
; #define GAS __attribute__((address_space(1)))
; __device__ __forceinline__ float bflo(unsigned w) { return __uint_as_float(w << 16); }
; __device__ __forceinline__ float bfhi(unsigned w) { return __uint_as_float(w & 0xffff0000u); }
; __device__ __forceinline__ f32x4 bperm_f4(int src4, f32x4 v) { return (f32x4){bperm_f(src4, v.x), bperm_f(src4, v.y), bperm_f(src4, v.z), bperm_f(src4, v.w)}; }
;     __device__ __forceinline__ void operator()(const pg8::f32x4 (&acc)[2][2][4][2], const pg8::Unit& u, int wr, int wc, int fr, int fq) const {
;     ...
;                     for (int bj = 0; bj < 2; ++bj) gt[m][bj] = *(const GAS u32x4*)(P + (size_t)(row0 + ai * 128 + m * 16) * NP + gcol + col0 + bj * 128);
;                 __builtin_amdgcn_sched_barrier(0);
; #pragma unroll
;                 for (int m = 0; m < 4; ++m)
; #pragma unroll
;                     for (int bj = 0; bj < 2; ++bj) {
;                         const u32x4 g = gt[m][bj]; const f32x4 a0 = bperm_f4(src4, acc[ai][bj][m][0]), a1 = bperm_f4(src4, acc[ai][bj][m][1]);
;                         float* gp = G1 + (size_t)(row0 + ai * 128 + m * 16) * DM + col0 + bj * 128;
;                         *(GAS f32x4*)gp = (f32x4){a0.x * bflo(g.x), a0.y * bfhi(g.x), a0.z * bflo(g.y), a0.w * bfhi(g.y)};
;                         *(GAS f32x4*)(gp + 4) = (f32x4){a1.x * bflo(g.z), a1.y * bfhi(g.z), a1.z * bflo(g.w), a1.w * bfhi(g.w)};
;                     }
;                 __builtin_amdgcn_sched_barrier(0);
;             }
	v_lshlrev_b32_e32 v190, 16, v206
	v_and_b32_e32 v191, 0xffff0000, v206
	v_lshl_add_u64 v[176:177], s[2:3], 0, v[176:177]
	s_waitcnt lgkmcnt(6)
	v_pk_mul_f32 v[190:191], v[190:191], v[184:185]
	v_lshlrev_b32_e32 v184, 16, v207
	v_and_b32_e32 v185, 0xffff0000, v207
	v_lshl_add_u64 v[176:177], v[176:177], 0, v[158:159]
	s_waitcnt lgkmcnt(4)
	v_pk_mul_f32 v[192:193], v[184:185], v[192:193]
	v_lshlrev_b32_e32 v184, 16, v208
	v_and_b32_e32 v185, 0xffff0000, v208
	global_store_dwordx4 v[176:177], v[190:193], off
	s_waitcnt lgkmcnt(2)
	s_nop 0
	v_pk_mul_f32 v[190:191], v[184:185], v[194:195]
	v_lshlrev_b32_e32 v184, 16, v209
	v_and_b32_e32 v185, 0xffff0000, v209
	s_waitcnt lgkmcnt(0)
	v_pk_mul_f32 v[192:193], v[184:185], v[196:197]
	global_store_dwordx4 v[176:177], v[190:193], off offset:16
	ds_bpermute_b32 v192, v179, v24
	ds_bpermute_b32 v193, v179, v25
	ds_bpermute_b32 v184, v179, v22
	ds_bpermute_b32 v185, v179, v23
	ds_bpermute_b32 v194, v179, v18
	ds_bpermute_b32 v195, v179, v19
	ds_bpermute_b32 v196, v179, v20
	ds_bpermute_b32 v197, v179, v21
	s_waitcnt vmcnt(12)
	v_lshlrev_b32_e32 v190, 16, v138
	v_and_b32_e32 v191, 0xffff0000, v138
	v_lshlrev_b32_e32 v138, 16, v139
	v_and_b32_e32 v139, 0xffff0000, v139
	s_waitcnt lgkmcnt(6)
	v_pk_mul_f32 v[192:193], v[138:139], v[192:193]
	v_lshlrev_b32_e32 v138, 16, v140
	v_and_b32_e32 v139, 0xffff0000, v140
	v_lshlrev_b32_e32 v140, 16, v141
	v_and_b32_e32 v141, 0xffff0000, v141
	s_waitcnt lgkmcnt(4)
	v_pk_mul_f32 v[190:191], v[190:191], v[184:185]
	s_waitcnt lgkmcnt(2)
	v_pk_mul_f32 v[138:139], v[138:139], v[194:195]
	s_waitcnt lgkmcnt(0)
	v_pk_mul_f32 v[140:141], v[140:141], v[196:197]
	global_store_dwordx4 v[176:177], v[190:193], off offset:512
	global_store_dwordx4 v[176:177], v[138:141], off offset:528
	ds_bpermute_b32 v140, v179, v14
	ds_bpermute_b32 v141, v179, v15
	ds_bpermute_b32 v176, v179, v16
	ds_bpermute_b32 v177, v179, v17
	ds_bpermute_b32 v184, v179, v10
	ds_bpermute_b32 v185, v179, v11
	ds_bpermute_b32 v190, v179, v12
	ds_bpermute_b32 v191, v179, v13
	v_lshlrev_b64 v[138:139], 13, v[154:155]
	v_lshl_add_u64 v[138:139], s[2:3], 0, v[138:139]
	v_lshl_add_u64 v[192:193], v[138:139], 0, v[158:159]
	s_waitcnt vmcnt(13)
	v_lshlrev_b32_e32 v138, 16, v134
	v_and_b32_e32 v139, 0xffff0000, v134
	v_lshlrev_b32_e32 v134, 16, v135
	v_and_b32_e32 v135, 0xffff0000, v135
	s_waitcnt lgkmcnt(6)
	v_pk_mul_f32 v[138:139], v[138:139], v[140:141]
	s_waitcnt lgkmcnt(4)
	v_pk_mul_f32 v[140:141], v[134:135], v[176:177]
	v_lshlrev_b32_e32 v134, 16, v136
	v_and_b32_e32 v135, 0xffff0000, v136
	v_lshlrev_b32_e32 v136, 16, v137
	v_and_b32_e32 v137, 0xffff0000, v137
	s_waitcnt lgkmcnt(2)
	v_pk_mul_f32 v[134:135], v[134:135], v[184:185]
	s_waitcnt lgkmcnt(0)
	v_pk_mul_f32 v[136:137], v[136:137], v[190:191]
	global_store_dwordx4 v[192:193], v[134:137], off offset:16
	ds_bpermute_b32 v136, v179, v8
	ds_bpermute_b32 v137, v179, v9
	global_store_dwordx4 v[192:193], v[138:141], off
	ds_bpermute_b32 v134, v179, v6
	ds_bpermute_b32 v135, v179, v7
	ds_bpermute_b32 v138, v179, v2
	ds_bpermute_b32 v139, v179, v3
	ds_bpermute_b32 v140, v179, v4
	ds_bpermute_b32 v141, v179, v5
	s_waitcnt vmcnt(14)
	v_lshlrev_b32_e32 v176, 16, v130
	v_and_b32_e32 v177, 0xffff0000, v130
	v_lshlrev_b32_e32 v130, 16, v131
	v_and_b32_e32 v131, 0xffff0000, v131
	s_waitcnt lgkmcnt(6)
	v_pk_mul_f32 v[136:137], v[130:131], v[136:137]
	v_lshlrev_b32_e32 v130, 16, v132
	v_and_b32_e32 v131, 0xffff0000, v132
	v_lshlrev_b32_e32 v132, 16, v133
	v_and_b32_e32 v133, 0xffff0000, v133
	s_waitcnt lgkmcnt(4)
	v_pk_mul_f32 v[134:135], v[176:177], v[134:135]
	s_waitcnt lgkmcnt(2)
	v_pk_mul_f32 v[130:131], v[130:131], v[138:139]
	s_waitcnt lgkmcnt(0)
	v_pk_mul_f32 v[132:133], v[132:133], v[140:141]
	global_store_dwordx4 v[192:193], v[134:137], off offset:512
	global_store_dwordx4 v[192:193], v[130:133], off offset:528
	s_cbranch_execz .LBB0_1120

; #define GAS __attribute__((address_space(1)))
; __device__ __forceinline__ float bflo(unsigned w) { return __uint_as_float(w << 16); }
; __device__ __forceinline__ float bfhi(unsigned w) { return __uint_as_float(w & 0xffff0000u); }
; __device__ __forceinline__ unsigned pk2(float lo, float hi) { unsigned r; asm("v_cvt_pk_bf16_f32 %0, %1, %2" : "=v"(r) : "v"(lo), "v"(hi)); return r; }
; __device__ __forceinline__ f32x4 bperm_f4(int src4, f32x4 v) { return (f32x4){bperm_f(src4, v.x), bperm_f(src4, v.y), bperm_f(src4, v.z), bperm_f(src4, v.w)}; }
;     __device__ __forceinline__ void operator()(const pg8::f32x4 (&acc)[2][2][4][2], const pg8::Unit& u, int wr, int wc, int fr, int fq) const {
;     ...
;             for (int ai = 0; ai < 2; ++ai)
; #pragma unroll
;                 for (int mp = 0; mp < 2; ++mp) {
;                     u32x4 gt[2][2]; f32x4 g1[2][2][2];
; #pragma unroll
;                     for (int mm = 0; mm < 2; ++mm)
; #pragma unroll
;                         for (int bj = 0; bj < 2; ++bj) { const int row = row0 + ai * 128 + (2 * mp + mm) * 16, c = col0 + bj * 128;
;                             gt[mm][bj] = *(const GAS u32x4*)(P + (size_t)row * NP + gcol + c);
;                             g1[mm][bj][0] = *(const GAS f32x4*)(G1 + (size_t)row * DM + c); g1[mm][bj][1] = *(const GAS f32x4*)(G1 + (size_t)row * DM + c + 4); }
;                     __builtin_amdgcn_sched_barrier(0);
; #pragma unroll
;                     for (int mm = 0; mm < 2; ++mm)
; #pragma unroll
;                         for (int bj = 0; bj < 2; ++bj) { const int m = 2 * mp + mm; const int row = row0 + ai * 128 + m * 16, c = col0 + bj * 128;
;                             const u32x4 g = gt[mm][bj]; const f32x4 a0 = bperm_f4(src4, acc[ai][bj][m][0]), a1 = bperm_f4(src4, acc[ai][bj][m][1]), h0 = g1[mm][bj][0], h1 = g1[mm][bj][1];
;                             u32x4 w; w.x = pk2(a0.x * bflo(g.x) + h0.x, a0.y * bfhi(g.x) + h0.y); w.y = pk2(a0.z * bflo(g.y) + h0.z, a0.w * bfhi(g.y) + h0.w);
;                             w.z = pk2(a1.x * bflo(g.z) + h1.x, a1.y * bfhi(g.z) + h1.y); w.w = pk2(a1.z * bflo(g.w) + h1.z, a1.w * bfhi(g.w) + h1.w);
;                             *(GAS u32x4*)(MB + (size_t)row * DM + c) = w; }
;                     __builtin_amdgcn_sched_barrier(0);
;                 }
.LBB0_1120:
	s_nop 0
	v_lshl_add_u64 v[130:131], s[8:9], 0, v[172:173]
	v_mov_b32_e32 v159, v1
	v_ashrrev_i32_e32 v169, 31, v168
	v_lshl_add_u64 v[130:131], v[130:131], 0, v[0:1]
	v_lshl_add_u64 v[140:141], v[174:175], 0, v[158:159]
	v_lshlrev_b64 v[176:177], 13, v[168:169]
	global_load_dwordx4 v[132:135], v[140:141], off offset:16 nt
	global_load_dwordx4 v[136:139], v[140:141], off nt
	global_load_dwordx4 v[172:175], v[130:131], off nt
	global_load_dwordx4 v[190:193], v[130:131], off offset:256 nt
	global_load_dwordx4 v[194:197], v[140:141], off offset:528 nt
	global_load_dwordx4 v[198:201], v[140:141], off offset:512 nt
	v_mov_b64_e32 v[130:131], s[8:9]
	v_lshl_add_u64 v[176:177], s[2:3], 0, v[176:177]
	v_mad_i64_i32 v[140:141], s[22:23], v168, s74, v[130:131]
	v_lshl_add_u64 v[176:177], v[176:177], 0, v[158:159]
	v_lshl_add_u64 v[140:141], v[140:141], 0, v[0:1]
	global_load_dwordx4 v[202:205], v[176:177], off offset:16 nt
	global_load_dwordx4 v[206:209], v[176:177], off nt
	global_load_dwordx4 v[210:213], v[140:141], off nt
	global_load_dwordx4 v[214:217], v[140:141], off offset:256 nt
	global_load_dwordx4 v[232:235], v[176:177], off offset:528 nt
	global_load_dwordx4 v[236:239], v[176:177], off offset:512 nt
	ds_bpermute_b32 v126, v179, v126
	ds_bpermute_b32 v129, v179, v129
	ds_bpermute_b32 v155, v179, v122
	ds_bpermute_b32 v157, v179, v123
	ds_bpermute_b32 v127, v179, v127
	ds_bpermute_b32 v161, v179, v124
	ds_bpermute_b32 v128, v179, v128
	ds_bpermute_b32 v125, v179, v125
	s_waitcnt vmcnt(0)
	v_lshlrev_b32_e32 v122, 16, v172
	v_and_b32_e32 v124, 0xffff0000, v173
	s_waitcnt lgkmcnt(7)
	v_fma_f32 v122, v122, v126, v136
	s_waitcnt lgkmcnt(6)
	v_fmac_f32_e32 v139, v124, v129
	v_lshlrev_b32_e32 v124, 16, v174
	v_and_b32_e32 v126, 0xffff0000, v174
	v_and_b32_e32 v123, 0xffff0000, v172
	s_waitcnt lgkmcnt(5)
	v_fma_f32 v124, v124, v155, v132
	s_waitcnt lgkmcnt(4)
	v_fma_f32 v126, v126, v157, v133
	s_waitcnt lgkmcnt(3)
	v_fma_f32 v123, v123, v127, v137
	v_cvt_pk_bf16_f32 v124, v124, v126
	v_lshlrev_b32_e32 v126, 16, v175
	v_lshlrev_b64 v[140:141], 12, v[170:171]
	v_cvt_pk_bf16_f32 v122, v122, v123
	v_lshlrev_b32_e32 v123, 16, v173
	s_waitcnt lgkmcnt(2)
	v_fma_f32 v126, v126, v161, v134
	v_and_b32_e32 v127, 0xffff0000, v175
	s_waitcnt lgkmcnt(1)
	v_fma_f32 v123, v123, v128, v138
	s_waitcnt lgkmcnt(0)
	v_fmac_f32_e32 v135, v127, v125
	v_cvt_pk_bf16_f32 v125, v126, v135
	v_lshl_add_u64 v[126:127], s[4:5], 0, v[140:141]
	v_cvt_pk_bf16_f32 v123, v123, v139
	v_lshl_add_u64 v[126:127], v[126:127], 0, v[0:1]
	ds_bpermute_b32 v118, v179, v118
	ds_bpermute_b32 v121, v179, v121
	global_store_dwordx4 v[126:127], v[122:125], off
	ds_bpermute_b32 v119, v179, v119
	ds_bpermute_b32 v122, v179, v114
	ds_bpermute_b32 v123, v179, v115
	ds_bpermute_b32 v120, v179, v120
	ds_bpermute_b32 v124, v179, v116
	ds_bpermute_b32 v117, v179, v117
	v_lshlrev_b32_e32 v114, 16, v190
	v_and_b32_e32 v116, 0xffff0000, v191
	s_waitcnt lgkmcnt(7)
	v_fma_f32 v114, v114, v118, v198
	v_and_b32_e32 v115, 0xffff0000, v190
	s_waitcnt lgkmcnt(6)
	v_fmac_f32_e32 v201, v116, v121
	v_lshlrev_b32_e32 v116, 16, v192
	v_and_b32_e32 v118, 0xffff0000, v192
	s_waitcnt lgkmcnt(5)
	v_fma_f32 v115, v115, v119, v199
	s_waitcnt lgkmcnt(4)
	v_fma_f32 v116, v116, v122, v194
	s_waitcnt lgkmcnt(3)
	v_fma_f32 v118, v118, v123, v195
	v_cvt_pk_bf16_f32 v114, v114, v115
	v_lshlrev_b32_e32 v115, 16, v191
	v_cvt_pk_bf16_f32 v116, v116, v118
	v_lshlrev_b32_e32 v118, 16, v193
	v_and_b32_e32 v119, 0xffff0000, v193
	s_waitcnt lgkmcnt(2)
	v_fma_f32 v115, v115, v120, v200
	s_waitcnt lgkmcnt(1)
	v_fma_f32 v118, v118, v124, v196
	s_waitcnt lgkmcnt(0)
	v_fmac_f32_e32 v197, v119, v117
	v_cvt_pk_bf16_f32 v117, v118, v197
	ds_bpermute_b32 v110, v179, v110
	ds_bpermute_b32 v113, v179, v113
	v_cvt_pk_bf16_f32 v115, v115, v201
	global_store_dwordx4 v[126:127], v[114:117], off offset:256
	ds_bpermute_b32 v116, v179, v106
	ds_bpermute_b32 v117, v179, v107
	ds_bpermute_b32 v111, v179, v111
	ds_bpermute_b32 v118, v179, v108
	ds_bpermute_b32 v112, v179, v112
	ds_bpermute_b32 v109, v179, v109
	v_lshlrev_b32_e32 v106, 16, v210
	v_and_b32_e32 v108, 0xffff0000, v211
	s_waitcnt lgkmcnt(7)
	v_fma_f32 v106, v106, v110, v206
	s_waitcnt lgkmcnt(6)
	v_fmac_f32_e32 v209, v108, v113
	v_lshlrev_b32_e32 v108, 16, v212
	v_and_b32_e32 v110, 0xffff0000, v212
	v_and_b32_e32 v107, 0xffff0000, v210
	s_waitcnt lgkmcnt(5)
	v_fma_f32 v108, v108, v116, v202
	s_waitcnt lgkmcnt(4)
	v_fma_f32 v110, v110, v117, v203
	s_waitcnt lgkmcnt(3)
	v_fma_f32 v107, v107, v111, v207
	v_cvt_pk_bf16_f32 v108, v108, v110
	v_lshlrev_b32_e32 v110, 16, v213
	v_lshlrev_b64 v[114:115], 12, v[168:169]
	v_cvt_pk_bf16_f32 v106, v106, v107
	v_lshlrev_b32_e32 v107, 16, v211
	s_waitcnt lgkmcnt(2)
	v_fma_f32 v110, v110, v118, v204
	v_and_b32_e32 v111, 0xffff0000, v213
	s_waitcnt lgkmcnt(1)
	v_fma_f32 v107, v107, v112, v208
	s_waitcnt lgkmcnt(0)
	v_fmac_f32_e32 v205, v111, v109
	v_cvt_pk_bf16_f32 v109, v110, v205
	v_lshl_add_u64 v[110:111], s[4:5], 0, v[114:115]
	v_cvt_pk_bf16_f32 v107, v107, v209
	v_lshl_add_u64 v[110:111], v[110:111], 0, v[0:1]
	ds_bpermute_b32 v102, v179, v102
	ds_bpermute_b32 v103, v179, v103
	ds_bpermute_b32 v105, v179, v105
	global_store_dwordx4 v[110:111], v[106:109], off
	ds_bpermute_b32 v106, v179, v98
	ds_bpermute_b32 v107, v179, v99
	ds_bpermute_b32 v104, v179, v104
	ds_bpermute_b32 v108, v179, v100
	ds_bpermute_b32 v101, v179, v101
	v_lshlrev_b32_e32 v98, 16, v214
	v_and_b32_e32 v99, 0xffff0000, v214
	v_and_b32_e32 v100, 0xffff0000, v215
	s_waitcnt lgkmcnt(7)
	v_fma_f32 v98, v98, v102, v236
	s_waitcnt lgkmcnt(6)
	v_fma_f32 v99, v99, v103, v237
	s_waitcnt lgkmcnt(5)
; #define GAS __attribute__((address_space(1)))
; __device__ __forceinline__ float bflo(unsigned w) { return __uint_as_float(w << 16); }
; __device__ __forceinline__ float bfhi(unsigned w) { return __uint_as_float(w & 0xffff0000u); }
; __device__ __forceinline__ unsigned pk2(float lo, float hi) { unsigned r; asm("v_cvt_pk_bf16_f32 %0, %1, %2" : "=v"(r) : "v"(lo), "v"(hi)); return r; }
; __device__ __forceinline__ f32x4 bperm_f4(int src4, f32x4 v) { return (f32x4){bperm_f(src4, v.x), bperm_f(src4, v.y), bperm_f(src4, v.z), bperm_f(src4, v.w)}; }
;     __device__ __forceinline__ void operator()(const pg8::f32x4 (&acc)[2][2][4][2], const pg8::Unit& u, int wr, int wc, int fr, int fq) const {
;     ...
;             for (int ai = 0; ai < 2; ++ai)
; #pragma unroll
;                 for (int mp = 0; mp < 2; ++mp) {
;                     u32x4 gt[2][2]; f32x4 g1[2][2][2];
; #pragma unroll
;                     for (int mm = 0; mm < 2; ++mm)
; #pragma unroll
;                         for (int bj = 0; bj < 2; ++bj) { const int row = row0 + ai * 128 + (2 * mp + mm) * 16, c = col0 + bj * 128;
;                             gt[mm][bj] = *(const GAS u32x4*)(P + (size_t)row * NP + gcol + c);
;                             g1[mm][bj][0] = *(const GAS f32x4*)(G1 + (size_t)row * DM + c); g1[mm][bj][1] = *(const GAS f32x4*)(G1 + (size_t)row * DM + c + 4); }
;                     __builtin_amdgcn_sched_barrier(0);
; #pragma unroll
;                     for (int mm = 0; mm < 2; ++mm)
; #pragma unroll
;                         for (int bj = 0; bj < 2; ++bj) { const int m = 2 * mp + mm; const int row = row0 + ai * 128 + m * 16, c = col0 + bj * 128;
;                             const u32x4 g = gt[mm][bj]; const f32x4 a0 = bperm_f4(src4, acc[ai][bj][m][0]), a1 = bperm_f4(src4, acc[ai][bj][m][1]), h0 = g1[mm][bj][0], h1 = g1[mm][bj][1];
;                             u32x4 w; w.x = pk2(a0.x * bflo(g.x) + h0.x, a0.y * bfhi(g.x) + h0.y); w.y = pk2(a0.z * bflo(g.y) + h0.z, a0.w * bfhi(g.y) + h0.w);
;                             w.z = pk2(a1.x * bflo(g.z) + h1.x, a1.y * bfhi(g.z) + h1.y); w.w = pk2(a1.z * bflo(g.w) + h1.z, a1.w * bfhi(g.w) + h1.w);
;                             *(GAS u32x4*)(MB + (size_t)row * DM + c) = w; }
;                     __builtin_amdgcn_sched_barrier(0);
;                 }
	v_fmac_f32_e32 v239, v100, v105
	v_lshlrev_b32_e32 v100, 16, v216
	v_and_b32_e32 v102, 0xffff0000, v216
	v_cvt_pk_bf16_f32 v98, v98, v99
	v_lshlrev_b32_e32 v99, 16, v215
	s_waitcnt lgkmcnt(4)
	v_fma_f32 v100, v100, v106, v232
	s_waitcnt lgkmcnt(3)
	v_fma_f32 v102, v102, v107, v233
	s_waitcnt lgkmcnt(2)
	v_fma_f32 v99, v99, v104, v238
	v_cvt_pk_bf16_f32 v100, v100, v102
	v_lshlrev_b32_e32 v102, 16, v217
	v_and_b32_e32 v103, 0xffff0000, v217
	v_cvt_pk_bf16_f32 v99, v99, v239
	s_waitcnt lgkmcnt(1)
	v_fma_f32 v102, v102, v108, v234
	s_waitcnt lgkmcnt(0)
	v_fmac_f32_e32 v235, v103, v101
	v_cvt_pk_bf16_f32 v101, v102, v235
	global_store_dwordx4 v[110:111], v[98:101], off offset:256
	v_ashrrev_i32_e32 v167, 31, v166
	v_ashrrev_i32_e32 v165, 31, v164
	v_lshlrev_b64 v[100:101], 13, v[166:167]
	v_lshlrev_b64 v[124:125], 13, v[164:165]
	v_mad_i64_i32 v[98:99], s[22:23], v166, s74, v[130:131]
	v_lshl_add_u64 v[100:101], s[2:3], 0, v[100:101]
	v_mad_i64_i32 v[122:123], s[22:23], v164, s74, v[130:131]
	v_lshl_add_u64 v[124:125], s[2:3], 0, v[124:125]
	v_lshl_add_u64 v[110:111], v[98:99], 0, v[0:1]
	v_lshl_add_u64 v[118:119], v[100:101], 0, v[158:159]
	v_lshl_add_u64 v[136:137], v[122:123], 0, v[0:1]
	v_lshl_add_u64 v[140:141], v[124:125], 0, v[158:159]
	global_load_dwordx4 v[98:101], v[118:119], off offset:16 nt
	global_load_dwordx4 v[102:105], v[118:119], off nt
	global_load_dwordx4 v[106:109], v[110:111], off nt
	s_nop 0
	global_load_dwordx4 v[110:113], v[110:111], off offset:256 nt
	s_nop 0
	global_load_dwordx4 v[114:117], v[118:119], off offset:528 nt
	s_nop 0
	global_load_dwordx4 v[118:121], v[118:119], off offset:512 nt
	s_nop 0
	global_load_dwordx4 v[122:125], v[140:141], off offset:16 nt
	global_load_dwordx4 v[126:129], v[140:141], off nt
	global_load_dwordx4 v[132:135], v[136:137], off nt
	s_nop 0
	global_load_dwordx4 v[136:139], v[136:137], off offset:256 nt
	s_nop 0
	global_load_dwordx4 v[168:171], v[140:141], off offset:528 nt
	global_load_dwordx4 v[172:175], v[140:141], off offset:512 nt
	ds_bpermute_b32 v94, v179, v94
	ds_bpermute_b32 v97, v179, v97
	ds_bpermute_b32 v155, v179, v90
	ds_bpermute_b32 v157, v179, v91
	ds_bpermute_b32 v95, v179, v95
	ds_bpermute_b32 v161, v179, v92
	ds_bpermute_b32 v96, v179, v96
	ds_bpermute_b32 v93, v179, v93
	s_waitcnt vmcnt(9)
	v_lshlrev_b32_e32 v90, 16, v106
	v_and_b32_e32 v92, 0xffff0000, v107
	s_waitcnt lgkmcnt(7)
	v_fma_f32 v90, v90, v94, v102
	s_waitcnt lgkmcnt(6)
	v_fmac_f32_e32 v105, v92, v97
	v_lshlrev_b32_e32 v92, 16, v108
	v_and_b32_e32 v94, 0xffff0000, v108
	v_and_b32_e32 v91, 0xffff0000, v106
	s_waitcnt lgkmcnt(5)
	v_fma_f32 v92, v92, v155, v98
	s_waitcnt lgkmcnt(4)
	v_fma_f32 v94, v94, v157, v99
	s_waitcnt lgkmcnt(3)
	v_fma_f32 v91, v91, v95, v103
	v_cvt_pk_bf16_f32 v92, v92, v94
	v_lshlrev_b32_e32 v94, 16, v109
	v_lshlrev_b64 v[140:141], 12, v[166:167]
	v_cvt_pk_bf16_f32 v90, v90, v91
	v_lshlrev_b32_e32 v91, 16, v107
	s_waitcnt lgkmcnt(2)
	v_fma_f32 v94, v94, v161, v100
	v_and_b32_e32 v95, 0xffff0000, v109
	s_waitcnt lgkmcnt(1)
	v_fma_f32 v91, v91, v96, v104
	s_waitcnt lgkmcnt(0)
	v_fmac_f32_e32 v101, v95, v93
	v_cvt_pk_bf16_f32 v93, v94, v101
	v_lshl_add_u64 v[94:95], s[4:5], 0, v[140:141]
	v_cvt_pk_bf16_f32 v91, v91, v105
	v_lshl_add_u64 v[94:95], v[94:95], 0, v[0:1]
	ds_bpermute_b32 v86, v179, v86
	ds_bpermute_b32 v89, v179, v89
	global_store_dwordx4 v[94:95], v[90:93], off
	ds_bpermute_b32 v87, v179, v87
	ds_bpermute_b32 v90, v179, v82
	ds_bpermute_b32 v91, v179, v83
	ds_bpermute_b32 v88, v179, v88
	ds_bpermute_b32 v92, v179, v84
	ds_bpermute_b32 v85, v179, v85
	s_waitcnt vmcnt(9)
	v_lshlrev_b32_e32 v82, 16, v110
	v_and_b32_e32 v84, 0xffff0000, v111
	s_waitcnt vmcnt(7) lgkmcnt(7)
	v_fma_f32 v82, v82, v86, v118
	v_and_b32_e32 v83, 0xffff0000, v110
	s_waitcnt lgkmcnt(6)
	v_fmac_f32_e32 v121, v84, v89
	v_lshlrev_b32_e32 v84, 16, v112
	v_and_b32_e32 v86, 0xffff0000, v112
	s_waitcnt lgkmcnt(5)
	v_fma_f32 v83, v83, v87, v119
	s_waitcnt lgkmcnt(4)
	v_fma_f32 v84, v84, v90, v114
	s_waitcnt lgkmcnt(3)
	v_fma_f32 v86, v86, v91, v115
	v_cvt_pk_bf16_f32 v82, v82, v83
	v_lshlrev_b32_e32 v83, 16, v111
	v_cvt_pk_bf16_f32 v84, v84, v86
	v_lshlrev_b32_e32 v86, 16, v113
	v_and_b32_e32 v87, 0xffff0000, v113
	s_waitcnt lgkmcnt(2)
	v_fma_f32 v83, v83, v88, v120
	s_waitcnt lgkmcnt(1)
	v_fma_f32 v86, v86, v92, v116
	s_waitcnt lgkmcnt(0)
	v_fmac_f32_e32 v117, v87, v85
	v_cvt_pk_bf16_f32 v85, v86, v117
	ds_bpermute_b32 v78, v179, v78
	ds_bpermute_b32 v81, v179, v81
	v_cvt_pk_bf16_f32 v83, v83, v121
	global_store_dwordx4 v[94:95], v[82:85], off offset:256
	ds_bpermute_b32 v84, v179, v74
	ds_bpermute_b32 v85, v179, v75
	ds_bpermute_b32 v79, v179, v79
	ds_bpermute_b32 v86, v179, v76
	ds_bpermute_b32 v80, v179, v80
	ds_bpermute_b32 v77, v179, v77
	s_waitcnt vmcnt(5)
	v_lshlrev_b32_e32 v74, 16, v132
	v_and_b32_e32 v76, 0xffff0000, v133
	s_waitcnt lgkmcnt(7)
	v_fma_f32 v74, v74, v78, v126
	s_waitcnt lgkmcnt(6)
	v_fmac_f32_e32 v129, v76, v81
	v_lshlrev_b32_e32 v76, 16, v134
	v_and_b32_e32 v78, 0xffff0000, v134
	v_and_b32_e32 v75, 0xffff0000, v132
	s_waitcnt lgkmcnt(5)
	v_fma_f32 v76, v76, v84, v122
	s_waitcnt lgkmcnt(4)
	v_fma_f32 v78, v78, v85, v123
	s_waitcnt lgkmcnt(3)
	v_fma_f32 v75, v75, v79, v127
	v_cvt_pk_bf16_f32 v76, v76, v78
	v_lshlrev_b32_e32 v78, 16, v135
	v_lshlrev_b64 v[82:83], 12, v[164:165]
	v_cvt_pk_bf16_f32 v74, v74, v75
	v_lshlrev_b32_e32 v75, 16, v133
	s_waitcnt lgkmcnt(2)
	v_fma_f32 v78, v78, v86, v124
	v_and_b32_e32 v79, 0xffff0000, v135
	s_waitcnt lgkmcnt(1)
	v_fma_f32 v75, v75, v80, v128
	s_waitcnt lgkmcnt(0)
; #define GAS __attribute__((address_space(1)))
; __device__ __forceinline__ float bflo(unsigned w) { return __uint_as_float(w << 16); }
; __device__ __forceinline__ float bfhi(unsigned w) { return __uint_as_float(w & 0xffff0000u); }
; __device__ __forceinline__ unsigned pk2(float lo, float hi) { unsigned r; asm("v_cvt_pk_bf16_f32 %0, %1, %2" : "=v"(r) : "v"(lo), "v"(hi)); return r; }
; __device__ __forceinline__ f32x4 bperm_f4(int src4, f32x4 v) { return (f32x4){bperm_f(src4, v.x), bperm_f(src4, v.y), bperm_f(src4, v.z), bperm_f(src4, v.w)}; }
;     __device__ __forceinline__ void operator()(const pg8::f32x4 (&acc)[2][2][4][2], const pg8::Unit& u, int wr, int wc, int fr, int fq) const {
;     ...
;             for (int ai = 0; ai < 2; ++ai)
; #pragma unroll
;                 for (int mp = 0; mp < 2; ++mp) {
;                     u32x4 gt[2][2]; f32x4 g1[2][2][2];
; #pragma unroll
;                     for (int mm = 0; mm < 2; ++mm)
; #pragma unroll
;                         for (int bj = 0; bj < 2; ++bj) { const int row = row0 + ai * 128 + (2 * mp + mm) * 16, c = col0 + bj * 128;
;                             gt[mm][bj] = *(const GAS u32x4*)(P + (size_t)row * NP + gcol + c);
;                             g1[mm][bj][0] = *(const GAS f32x4*)(G1 + (size_t)row * DM + c); g1[mm][bj][1] = *(const GAS f32x4*)(G1 + (size_t)row * DM + c + 4); }
;                     __builtin_amdgcn_sched_barrier(0);
; #pragma unroll
;                     for (int mm = 0; mm < 2; ++mm)
; #pragma unroll
;                         for (int bj = 0; bj < 2; ++bj) { const int m = 2 * mp + mm; const int row = row0 + ai * 128 + m * 16, c = col0 + bj * 128;
;                             const u32x4 g = gt[mm][bj]; const f32x4 a0 = bperm_f4(src4, acc[ai][bj][m][0]), a1 = bperm_f4(src4, acc[ai][bj][m][1]), h0 = g1[mm][bj][0], h1 = g1[mm][bj][1];
;                             u32x4 w; w.x = pk2(a0.x * bflo(g.x) + h0.x, a0.y * bfhi(g.x) + h0.y); w.y = pk2(a0.z * bflo(g.y) + h0.z, a0.w * bfhi(g.y) + h0.w);
;                             w.z = pk2(a1.x * bflo(g.z) + h1.x, a1.y * bfhi(g.z) + h1.y); w.w = pk2(a1.z * bflo(g.w) + h1.z, a1.w * bfhi(g.w) + h1.w);
;                             *(GAS u32x4*)(MB + (size_t)row * DM + c) = w; }
;                     __builtin_amdgcn_sched_barrier(0);
;                 }
	v_fmac_f32_e32 v125, v79, v77
	v_cvt_pk_bf16_f32 v77, v78, v125
	v_lshl_add_u64 v[78:79], s[4:5], 0, v[82:83]
	v_cvt_pk_bf16_f32 v75, v75, v129
	v_lshl_add_u64 v[78:79], v[78:79], 0, v[0:1]
	ds_bpermute_b32 v70, v179, v70
	ds_bpermute_b32 v71, v179, v71
	ds_bpermute_b32 v73, v179, v73
	global_store_dwordx4 v[78:79], v[74:77], off
	ds_bpermute_b32 v74, v179, v66
	ds_bpermute_b32 v75, v179, v67
	ds_bpermute_b32 v72, v179, v72
	ds_bpermute_b32 v76, v179, v68
	ds_bpermute_b32 v69, v179, v69
	s_waitcnt vmcnt(5)
	v_lshlrev_b32_e32 v66, 16, v136
	v_and_b32_e32 v67, 0xffff0000, v136
	v_and_b32_e32 v68, 0xffff0000, v137
	s_waitcnt vmcnt(3) lgkmcnt(7)
	v_fma_f32 v66, v66, v70, v172
	s_waitcnt lgkmcnt(6)
	v_fma_f32 v67, v67, v71, v173
	s_waitcnt lgkmcnt(5)
	v_fmac_f32_e32 v175, v68, v73
	v_lshlrev_b32_e32 v68, 16, v138
	v_and_b32_e32 v70, 0xffff0000, v138
	v_cvt_pk_bf16_f32 v66, v66, v67
	v_lshlrev_b32_e32 v67, 16, v137
	s_waitcnt lgkmcnt(4)
	v_fma_f32 v68, v68, v74, v168
	s_waitcnt lgkmcnt(3)
	v_fma_f32 v70, v70, v75, v169
	s_waitcnt lgkmcnt(2)
	v_fma_f32 v67, v67, v72, v174
	v_cvt_pk_bf16_f32 v68, v68, v70
	v_lshlrev_b32_e32 v70, 16, v139
	v_and_b32_e32 v71, 0xffff0000, v139
	v_cvt_pk_bf16_f32 v67, v67, v175
	s_waitcnt lgkmcnt(1)
	v_fma_f32 v70, v70, v76, v170
	s_waitcnt lgkmcnt(0)
	v_fmac_f32_e32 v171, v71, v69
	v_cvt_pk_bf16_f32 v69, v70, v171
	global_store_dwordx4 v[78:79], v[66:69], off offset:256
	v_ashrrev_i32_e32 v163, 31, v162
	v_ashrrev_i32_e32 v161, 31, v160
	v_lshlrev_b64 v[68:69], 13, v[162:163]
	v_lshlrev_b64 v[92:93], 13, v[160:161]
	v_mad_i64_i32 v[66:67], s[22:23], v162, s74, v[130:131]
	v_lshl_add_u64 v[68:69], s[2:3], 0, v[68:69]
	v_mad_i64_i32 v[90:91], s[22:23], v160, s74, v[130:131]
	v_lshl_add_u64 v[92:93], s[2:3], 0, v[92:93]
	v_lshl_add_u64 v[78:79], v[66:67], 0, v[0:1]
	v_lshl_add_u64 v[86:87], v[68:69], 0, v[158:159]
	v_lshl_add_u64 v[102:103], v[90:91], 0, v[0:1]
	v_lshl_add_u64 v[110:111], v[92:93], 0, v[158:159]
	global_load_dwordx4 v[66:69], v[86:87], off offset:16 nt
	global_load_dwordx4 v[70:73], v[86:87], off nt
	global_load_dwordx4 v[74:77], v[78:79], off nt
	s_nop 0
	global_load_dwordx4 v[78:81], v[78:79], off offset:256 nt
	s_nop 0
	global_load_dwordx4 v[82:85], v[86:87], off offset:528 nt
	s_nop 0
	global_load_dwordx4 v[86:89], v[86:87], off offset:512 nt
	s_nop 0
	global_load_dwordx4 v[90:93], v[110:111], off offset:16 nt
	global_load_dwordx4 v[94:97], v[110:111], off nt
	global_load_dwordx4 v[98:101], v[102:103], off nt
	s_nop 0
	global_load_dwordx4 v[102:105], v[102:103], off offset:256 nt
	s_nop 0
	global_load_dwordx4 v[106:109], v[110:111], off offset:528 nt
	s_nop 0
	global_load_dwordx4 v[110:113], v[110:111], off offset:512 nt
	ds_bpermute_b32 v62, v179, v62
	ds_bpermute_b32 v65, v179, v65
	ds_bpermute_b32 v116, v179, v58
	ds_bpermute_b32 v117, v179, v59
	ds_bpermute_b32 v63, v179, v63
	ds_bpermute_b32 v118, v179, v60
	ds_bpermute_b32 v64, v179, v64
	ds_bpermute_b32 v61, v179, v61
	s_waitcnt vmcnt(9)
	v_lshlrev_b32_e32 v58, 16, v74
	v_and_b32_e32 v60, 0xffff0000, v75
	s_waitcnt lgkmcnt(7)
	v_fma_f32 v58, v58, v62, v70
	s_waitcnt lgkmcnt(6)
	v_fmac_f32_e32 v73, v60, v65
	v_lshlrev_b32_e32 v60, 16, v76
	v_and_b32_e32 v62, 0xffff0000, v76
	v_and_b32_e32 v59, 0xffff0000, v74
	s_waitcnt lgkmcnt(5)
	v_fma_f32 v60, v60, v116, v66
	s_waitcnt lgkmcnt(4)
	v_fma_f32 v62, v62, v117, v67
	s_waitcnt lgkmcnt(3)
	v_fma_f32 v59, v59, v63, v71
	v_cvt_pk_bf16_f32 v60, v60, v62
	v_lshlrev_b32_e32 v62, 16, v77
	v_lshlrev_b64 v[114:115], 12, v[162:163]
	v_cvt_pk_bf16_f32 v58, v58, v59
	v_lshlrev_b32_e32 v59, 16, v75
	s_waitcnt lgkmcnt(2)
	v_fma_f32 v62, v62, v118, v68
	v_and_b32_e32 v63, 0xffff0000, v77
	s_waitcnt lgkmcnt(1)
	v_fma_f32 v59, v59, v64, v72
	s_waitcnt lgkmcnt(0)
	v_fmac_f32_e32 v69, v63, v61
	v_cvt_pk_bf16_f32 v61, v62, v69
	v_lshl_add_u64 v[62:63], s[4:5], 0, v[114:115]
	v_cvt_pk_bf16_f32 v59, v59, v73
	v_lshl_add_u64 v[62:63], v[62:63], 0, v[0:1]
	ds_bpermute_b32 v54, v179, v54
	ds_bpermute_b32 v57, v179, v57
	global_store_dwordx4 v[62:63], v[58:61], off
	ds_bpermute_b32 v55, v179, v55
	ds_bpermute_b32 v58, v179, v50
	ds_bpermute_b32 v59, v179, v51
	ds_bpermute_b32 v56, v179, v56
	ds_bpermute_b32 v60, v179, v52
	ds_bpermute_b32 v53, v179, v53
	s_waitcnt vmcnt(9)
	v_lshlrev_b32_e32 v50, 16, v78
	v_and_b32_e32 v52, 0xffff0000, v79
	s_waitcnt vmcnt(7) lgkmcnt(7)
	v_fma_f32 v50, v50, v54, v86
	v_and_b32_e32 v51, 0xffff0000, v78
	s_waitcnt lgkmcnt(6)
	v_fmac_f32_e32 v89, v52, v57
	v_lshlrev_b32_e32 v52, 16, v80
	v_and_b32_e32 v54, 0xffff0000, v80
	s_waitcnt lgkmcnt(5)
	v_fma_f32 v51, v51, v55, v87
	s_waitcnt lgkmcnt(4)
	v_fma_f32 v52, v52, v58, v82
	s_waitcnt lgkmcnt(3)
	v_fma_f32 v54, v54, v59, v83
	v_cvt_pk_bf16_f32 v50, v50, v51
	v_lshlrev_b32_e32 v51, 16, v79
	v_cvt_pk_bf16_f32 v52, v52, v54
	v_lshlrev_b32_e32 v54, 16, v81
	v_and_b32_e32 v55, 0xffff0000, v81
	s_waitcnt lgkmcnt(2)
	v_fma_f32 v51, v51, v56, v88
	s_waitcnt lgkmcnt(1)
	v_fma_f32 v54, v54, v60, v84
	s_waitcnt lgkmcnt(0)
	v_fmac_f32_e32 v85, v55, v53
	v_cvt_pk_bf16_f32 v53, v54, v85
	ds_bpermute_b32 v46, v179, v46
	ds_bpermute_b32 v49, v179, v49
	v_cvt_pk_bf16_f32 v51, v51, v89
	global_store_dwordx4 v[62:63], v[50:53], off offset:256
	ds_bpermute_b32 v52, v179, v42
	ds_bpermute_b32 v53, v179, v43
	ds_bpermute_b32 v47, v179, v47
	ds_bpermute_b32 v54, v179, v44
	ds_bpermute_b32 v48, v179, v48
	ds_bpermute_b32 v45, v179, v45
	s_waitcnt vmcnt(5)
	v_lshlrev_b32_e32 v42, 16, v98
	v_and_b32_e32 v44, 0xffff0000, v99
	s_waitcnt lgkmcnt(7)
	v_fma_f32 v42, v42, v46, v94
	s_waitcnt lgkmcnt(6)
; #define GAS __attribute__((address_space(1)))
; __device__ __forceinline__ float bflo(unsigned w) { return __uint_as_float(w << 16); }
; __device__ __forceinline__ float bfhi(unsigned w) { return __uint_as_float(w & 0xffff0000u); }
; __device__ __forceinline__ unsigned pk2(float lo, float hi) { unsigned r; asm("v_cvt_pk_bf16_f32 %0, %1, %2" : "=v"(r) : "v"(lo), "v"(hi)); return r; }
; __device__ __forceinline__ f32x4 bperm_f4(int src4, f32x4 v) { return (f32x4){bperm_f(src4, v.x), bperm_f(src4, v.y), bperm_f(src4, v.z), bperm_f(src4, v.w)}; }
;     __device__ __forceinline__ void operator()(const pg8::f32x4 (&acc)[2][2][4][2], const pg8::Unit& u, int wr, int wc, int fr, int fq) const {
;     ...
;             for (int ai = 0; ai < 2; ++ai)
; #pragma unroll
;                 for (int mp = 0; mp < 2; ++mp) {
;                     u32x4 gt[2][2]; f32x4 g1[2][2][2];
; #pragma unroll
;                     for (int mm = 0; mm < 2; ++mm)
; #pragma unroll
;                         for (int bj = 0; bj < 2; ++bj) { const int row = row0 + ai * 128 + (2 * mp + mm) * 16, c = col0 + bj * 128;
;                             gt[mm][bj] = *(const GAS u32x4*)(P + (size_t)row * NP + gcol + c);
;                             g1[mm][bj][0] = *(const GAS f32x4*)(G1 + (size_t)row * DM + c); g1[mm][bj][1] = *(const GAS f32x4*)(G1 + (size_t)row * DM + c + 4); }
;                     __builtin_amdgcn_sched_barrier(0);
; #pragma unroll
;                     for (int mm = 0; mm < 2; ++mm)
; #pragma unroll
;                         for (int bj = 0; bj < 2; ++bj) { const int m = 2 * mp + mm; const int row = row0 + ai * 128 + m * 16, c = col0 + bj * 128;
;                             const u32x4 g = gt[mm][bj]; const f32x4 a0 = bperm_f4(src4, acc[ai][bj][m][0]), a1 = bperm_f4(src4, acc[ai][bj][m][1]), h0 = g1[mm][bj][0], h1 = g1[mm][bj][1];
;                             u32x4 w; w.x = pk2(a0.x * bflo(g.x) + h0.x, a0.y * bfhi(g.x) + h0.y); w.y = pk2(a0.z * bflo(g.y) + h0.z, a0.w * bfhi(g.y) + h0.w);
;                             w.z = pk2(a1.x * bflo(g.z) + h1.x, a1.y * bfhi(g.z) + h1.y); w.w = pk2(a1.z * bflo(g.w) + h1.z, a1.w * bfhi(g.w) + h1.w);
;                             *(GAS u32x4*)(MB + (size_t)row * DM + c) = w; }
;                     __builtin_amdgcn_sched_barrier(0);
;                 }
	v_fmac_f32_e32 v97, v44, v49
	v_lshlrev_b32_e32 v44, 16, v100
	v_and_b32_e32 v46, 0xffff0000, v100
	v_and_b32_e32 v43, 0xffff0000, v98
	s_waitcnt lgkmcnt(5)
	v_fma_f32 v44, v44, v52, v90
	s_waitcnt lgkmcnt(4)
	v_fma_f32 v46, v46, v53, v91
	s_waitcnt lgkmcnt(3)
	v_fma_f32 v43, v43, v47, v95
	v_cvt_pk_bf16_f32 v44, v44, v46
	v_lshlrev_b32_e32 v46, 16, v101
	v_lshlrev_b64 v[50:51], 12, v[160:161]
	v_cvt_pk_bf16_f32 v42, v42, v43
	v_lshlrev_b32_e32 v43, 16, v99
	s_waitcnt lgkmcnt(2)
	v_fma_f32 v46, v46, v54, v92
	v_and_b32_e32 v47, 0xffff0000, v101
	s_waitcnt lgkmcnt(1)
	v_fma_f32 v43, v43, v48, v96
	s_waitcnt lgkmcnt(0)
	v_fmac_f32_e32 v93, v47, v45
	v_cvt_pk_bf16_f32 v45, v46, v93
	v_lshl_add_u64 v[46:47], s[4:5], 0, v[50:51]
	v_cvt_pk_bf16_f32 v43, v43, v97
	v_lshl_add_u64 v[46:47], v[46:47], 0, v[0:1]
	ds_bpermute_b32 v38, v179, v38
	ds_bpermute_b32 v39, v179, v39
	ds_bpermute_b32 v41, v179, v41
	global_store_dwordx4 v[46:47], v[42:45], off
	ds_bpermute_b32 v42, v179, v34
	ds_bpermute_b32 v43, v179, v35
	ds_bpermute_b32 v40, v179, v40
	ds_bpermute_b32 v44, v179, v36
	ds_bpermute_b32 v37, v179, v37
	s_waitcnt vmcnt(5)
	v_lshlrev_b32_e32 v34, 16, v102
	v_and_b32_e32 v35, 0xffff0000, v102
	v_and_b32_e32 v36, 0xffff0000, v103
	s_waitcnt vmcnt(3) lgkmcnt(7)
	v_fma_f32 v34, v34, v38, v110
	s_waitcnt lgkmcnt(6)
	v_fma_f32 v35, v35, v39, v111
	s_waitcnt lgkmcnt(5)
	v_fmac_f32_e32 v113, v36, v41
	v_lshlrev_b32_e32 v36, 16, v104
	v_and_b32_e32 v38, 0xffff0000, v104
	v_cvt_pk_bf16_f32 v34, v34, v35
	v_lshlrev_b32_e32 v35, 16, v103
	s_waitcnt lgkmcnt(4)
	v_fma_f32 v36, v36, v42, v106
	s_waitcnt lgkmcnt(3)
	v_fma_f32 v38, v38, v43, v107
	s_waitcnt lgkmcnt(2)
	v_fma_f32 v35, v35, v40, v112
	v_cvt_pk_bf16_f32 v36, v36, v38
	v_lshlrev_b32_e32 v38, 16, v105
	v_and_b32_e32 v39, 0xffff0000, v105
	v_cvt_pk_bf16_f32 v35, v35, v113
	s_waitcnt lgkmcnt(1)
	v_fma_f32 v38, v38, v44, v108
	s_waitcnt lgkmcnt(0)
	v_fmac_f32_e32 v109, v39, v37
	v_cvt_pk_bf16_f32 v37, v38, v109
	global_store_dwordx4 v[46:47], v[34:37], off offset:256
	v_ashrrev_i32_e32 v157, 31, v156
	v_ashrrev_i32_e32 v155, 31, v154
	v_lshlrev_b64 v[36:37], 13, v[156:157]
	v_lshlrev_b64 v[60:61], 13, v[154:155]
	v_mad_i64_i32 v[34:35], s[22:23], v156, s74, v[130:131]
	v_lshl_add_u64 v[36:37], s[2:3], 0, v[36:37]
	v_mad_i64_i32 v[58:59], s[22:23], v154, s74, v[130:131]
	v_lshl_add_u64 v[60:61], s[2:3], 0, v[60:61]
	v_lshl_add_u64 v[46:47], v[34:35], 0, v[0:1]
	v_lshl_add_u64 v[54:55], v[36:37], 0, v[158:159]
	v_lshl_add_u64 v[70:71], v[58:59], 0, v[0:1]
	v_lshl_add_u64 v[78:79], v[60:61], 0, v[158:159]
	global_load_dwordx4 v[34:37], v[54:55], off offset:16 nt
	global_load_dwordx4 v[38:41], v[54:55], off nt
	global_load_dwordx4 v[42:45], v[46:47], off nt
	s_nop 0
	global_load_dwordx4 v[46:49], v[46:47], off offset:256 nt
	s_nop 0
	global_load_dwordx4 v[50:53], v[54:55], off offset:528 nt
	s_nop 0
	global_load_dwordx4 v[54:57], v[54:55], off offset:512 nt
	s_nop 0
	global_load_dwordx4 v[58:61], v[78:79], off offset:16 nt
	global_load_dwordx4 v[62:65], v[78:79], off nt
	global_load_dwordx4 v[66:69], v[70:71], off nt
	s_nop 0
	global_load_dwordx4 v[70:73], v[70:71], off offset:256 nt
	s_nop 0
	global_load_dwordx4 v[74:77], v[78:79], off offset:528 nt
	s_nop 0
	global_load_dwordx4 v[78:81], v[78:79], off offset:512 nt
	ds_bpermute_b32 v30, v179, v30
	ds_bpermute_b32 v33, v179, v33
	ds_bpermute_b32 v84, v179, v26
	ds_bpermute_b32 v85, v179, v27
	ds_bpermute_b32 v31, v179, v31
	ds_bpermute_b32 v86, v179, v28
	ds_bpermute_b32 v32, v179, v32
	ds_bpermute_b32 v29, v179, v29
	s_waitcnt vmcnt(9)
	v_lshlrev_b32_e32 v26, 16, v42
	v_and_b32_e32 v28, 0xffff0000, v43
	s_waitcnt lgkmcnt(7)
	v_fma_f32 v26, v26, v30, v38
	s_waitcnt lgkmcnt(6)
	v_fmac_f32_e32 v41, v28, v33
	v_lshlrev_b32_e32 v28, 16, v44
	v_and_b32_e32 v30, 0xffff0000, v44
	v_and_b32_e32 v27, 0xffff0000, v42
	s_waitcnt lgkmcnt(5)
	v_fma_f32 v28, v28, v84, v34
	s_waitcnt lgkmcnt(4)
	v_fma_f32 v30, v30, v85, v35
	s_waitcnt lgkmcnt(3)
	v_fma_f32 v27, v27, v31, v39
	v_cvt_pk_bf16_f32 v28, v28, v30
	v_lshlrev_b32_e32 v30, 16, v45
	v_lshlrev_b64 v[82:83], 12, v[156:157]
	v_cvt_pk_bf16_f32 v26, v26, v27
	v_lshlrev_b32_e32 v27, 16, v43
	s_waitcnt lgkmcnt(2)
; #define GAS __attribute__((address_space(1)))
; __device__ __forceinline__ float bflo(unsigned w) { return __uint_as_float(w << 16); }
; __device__ __forceinline__ float bfhi(unsigned w) { return __uint_as_float(w & 0xffff0000u); }
; __device__ __forceinline__ unsigned pk2(float lo, float hi) { unsigned r; asm("v_cvt_pk_bf16_f32 %0, %1, %2" : "=v"(r) : "v"(lo), "v"(hi)); return r; }
; __device__ __forceinline__ f32x4 bperm_f4(int src4, f32x4 v) { return (f32x4){bperm_f(src4, v.x), bperm_f(src4, v.y), bperm_f(src4, v.z), bperm_f(src4, v.w)}; }
;     __device__ __forceinline__ void operator()(const pg8::f32x4 (&acc)[2][2][4][2], const pg8::Unit& u, int wr, int wc, int fr, int fq) const {
;     ...
;                         for (int bj = 0; bj < 2; ++bj) { const int m = 2 * mp + mm; const int row = row0 + ai * 128 + m * 16, c = col0 + bj * 128;
;                             const u32x4 g = gt[mm][bj]; const f32x4 a0 = bperm_f4(src4, acc[ai][bj][m][0]), a1 = bperm_f4(src4, acc[ai][bj][m][1]), h0 = g1[mm][bj][0], h1 = g1[mm][bj][1];
;                             u32x4 w; w.x = pk2(a0.x * bflo(g.x) + h0.x, a0.y * bfhi(g.x) + h0.y); w.y = pk2(a0.z * bflo(g.y) + h0.z, a0.w * bfhi(g.y) + h0.w);
;                             w.z = pk2(a1.x * bflo(g.z) + h1.x, a1.y * bfhi(g.z) + h1.y); w.w = pk2(a1.z * bflo(g.w) + h1.z, a1.w * bfhi(g.w) + h1.w);
;                             *(GAS u32x4*)(MB + (size_t)row * DM + c) = w; }
	v_fma_f32 v30, v30, v86, v36
	v_and_b32_e32 v31, 0xffff0000, v45
	s_waitcnt lgkmcnt(1)
	v_fma_f32 v27, v27, v32, v40
	s_waitcnt lgkmcnt(0)
	v_fmac_f32_e32 v37, v31, v29
	v_cvt_pk_bf16_f32 v29, v30, v37
	v_lshl_add_u64 v[30:31], s[4:5], 0, v[82:83]
	v_cvt_pk_bf16_f32 v27, v27, v41
	v_lshl_add_u64 v[30:31], v[30:31], 0, v[0:1]
	ds_bpermute_b32 v22, v179, v22
	ds_bpermute_b32 v25, v179, v25
	global_store_dwordx4 v[30:31], v[26:29], off
	ds_bpermute_b32 v23, v179, v23
	ds_bpermute_b32 v26, v179, v18
	ds_bpermute_b32 v27, v179, v19
	ds_bpermute_b32 v24, v179, v24
	ds_bpermute_b32 v28, v179, v20
	ds_bpermute_b32 v21, v179, v21
	s_waitcnt vmcnt(9)
	v_lshlrev_b32_e32 v18, 16, v46
	v_and_b32_e32 v20, 0xffff0000, v47
	s_waitcnt vmcnt(7) lgkmcnt(7)
	v_fma_f32 v18, v18, v22, v54
	v_and_b32_e32 v19, 0xffff0000, v46
	s_waitcnt lgkmcnt(6)
	v_fmac_f32_e32 v57, v20, v25
	v_lshlrev_b32_e32 v20, 16, v48
	v_and_b32_e32 v22, 0xffff0000, v48
	s_waitcnt lgkmcnt(5)
	v_fma_f32 v19, v19, v23, v55
	s_waitcnt lgkmcnt(4)
	v_fma_f32 v20, v20, v26, v50
	s_waitcnt lgkmcnt(3)
	v_fma_f32 v22, v22, v27, v51
	v_cvt_pk_bf16_f32 v18, v18, v19
	v_lshlrev_b32_e32 v19, 16, v47
	v_cvt_pk_bf16_f32 v20, v20, v22
	v_lshlrev_b32_e32 v22, 16, v49
	v_and_b32_e32 v23, 0xffff0000, v49
	s_waitcnt lgkmcnt(2)
	v_fma_f32 v19, v19, v24, v56
	s_waitcnt lgkmcnt(1)
	v_fma_f32 v22, v22, v28, v52
	s_waitcnt lgkmcnt(0)
	v_fmac_f32_e32 v53, v23, v21
	v_cvt_pk_bf16_f32 v21, v22, v53
	ds_bpermute_b32 v14, v179, v14
	ds_bpermute_b32 v17, v179, v17
	v_cvt_pk_bf16_f32 v19, v19, v57
	global_store_dwordx4 v[30:31], v[18:21], off offset:256
	ds_bpermute_b32 v20, v179, v10
	ds_bpermute_b32 v21, v179, v11
	ds_bpermute_b32 v15, v179, v15
	ds_bpermute_b32 v22, v179, v12
	ds_bpermute_b32 v13, v179, v13
	s_waitcnt vmcnt(5)
	v_lshlrev_b32_e32 v10, 16, v66
	v_and_b32_e32 v12, 0xffff0000, v67
	s_waitcnt lgkmcnt(6)
	v_fma_f32 v10, v10, v14, v62
	s_waitcnt lgkmcnt(5)
	v_fmac_f32_e32 v65, v12, v17
	v_lshlrev_b32_e32 v12, 16, v68
	v_and_b32_e32 v14, 0xffff0000, v68
	s_waitcnt lgkmcnt(4)
	v_fma_f32 v12, v12, v20, v58
	s_waitcnt lgkmcnt(3)
	v_fma_f32 v14, v14, v21, v59
	v_and_b32_e32 v11, 0xffff0000, v66
	v_cvt_pk_bf16_f32 v12, v12, v14
	v_lshlrev_b32_e32 v14, 16, v69
	v_lshlrev_b64 v[18:19], 12, v[154:155]
	s_waitcnt lgkmcnt(2)
	v_fma_f32 v11, v11, v15, v63
	s_waitcnt lgkmcnt(1)
	v_fma_f32 v14, v14, v22, v60
	v_and_b32_e32 v15, 0xffff0000, v69
	ds_bpermute_b32 v16, v179, v16
	s_waitcnt lgkmcnt(1)
	v_fmac_f32_e32 v61, v15, v13
	v_cvt_pk_bf16_f32 v13, v14, v61
	v_lshl_add_u64 v[14:15], s[4:5], 0, v[18:19]
	v_lshl_add_u64 v[14:15], v[14:15], 0, v[0:1]
	ds_bpermute_b32 v0, v179, v6
	ds_bpermute_b32 v6, v179, v7
	v_cvt_pk_bf16_f32 v10, v10, v11
	v_lshlrev_b32_e32 v11, 16, v67
	ds_bpermute_b32 v7, v179, v8
	s_waitcnt lgkmcnt(3)
	v_fma_f32 v11, v11, v16, v64
	ds_bpermute_b32 v8, v179, v9
	ds_bpermute_b32 v9, v179, v2
	s_waitcnt vmcnt(4)
	v_lshlrev_b32_e32 v2, 16, v70
	v_cvt_pk_bf16_f32 v11, v11, v65
	global_store_dwordx4 v[14:15], v[10:13], off
	ds_bpermute_b32 v10, v179, v3
	s_waitcnt vmcnt(3) lgkmcnt(5)
	v_fma_f32 v0, v2, v0, v78
	v_and_b32_e32 v2, 0xffff0000, v70
	s_waitcnt lgkmcnt(4)
	v_fma_f32 v2, v2, v6, v79
	ds_bpermute_b32 v11, v179, v4
	ds_bpermute_b32 v5, v179, v5
	v_cvt_pk_bf16_f32 v2, v0, v2
	v_lshlrev_b32_e32 v0, 16, v71
	s_waitcnt lgkmcnt(5)
	v_fma_f32 v0, v0, v7, v80
	v_and_b32_e32 v3, 0xffff0000, v71
	s_waitcnt lgkmcnt(4)
	v_fmac_f32_e32 v81, v3, v8
	v_cvt_pk_bf16_f32 v3, v0, v81
	v_lshlrev_b32_e32 v0, 16, v72
	v_and_b32_e32 v4, 0xffff0000, v72
	s_waitcnt lgkmcnt(3)
	v_fma_f32 v0, v0, v9, v74
	s_waitcnt lgkmcnt(2)
	v_fma_f32 v4, v4, v10, v75
	v_cvt_pk_bf16_f32 v4, v0, v4
	v_lshlrev_b32_e32 v0, 16, v73
	v_and_b32_e32 v6, 0xffff0000, v73
	s_waitcnt lgkmcnt(1)
	v_fma_f32 v0, v0, v11, v76
	s_waitcnt lgkmcnt(0)
	v_fmac_f32_e32 v77, v6, v5
	v_cvt_pk_bf16_f32 v5, v0, v77
	global_store_dwordx4 v[14:15], v[2:5], off offset:256
	s_andn2_b64 vcc, exec, s[18:19]
	s_mov_b64 s[18:19], -1
	s_cbranch_vccnz .LBB0_1109

; #define GAS __attribute__((address_space(1)))
; __device__ __forceinline__ unsigned pk2(float lo, float hi) { unsigned r; asm("v_cvt_pk_bf16_f32 %0, %1, %2" : "=v"(r) : "v"(lo), "v"(hi)); return r; }
; __device__ __forceinline__ f32x4 bperm_f4(int src4, f32x4 v) { return (f32x4){bperm_f(src4, v.x), bperm_f(src4, v.y), bperm_f(src4, v.z), bperm_f(src4, v.w)}; }
;     __device__ __forceinline__ void operator()(const pg8::f32x4 (&acc)[2][2][4][2], const pg8::Unit& u, int wr, int wc, int fr, int fq) const {
;     ...
;         for (int ai = 0; ai < 2; ++ai) {
;             f32x4 xo[4][2][2];
; #pragma unroll
;             for (int m = 0; m < 4; ++m)
; #pragma unroll
;                 for (int bj = 0; bj < 2; ++bj) { const size_t off = (size_t)(row0 + ai * 128 + m * 16) * DM + col0 + bj * 128; xo[m][bj][0] = *(const GAS f32x4*)(xold + off); xo[m][bj][1] = *(const GAS f32x4*)(xold + off + 4); }
;             __builtin_amdgcn_sched_barrier(0);
; #pragma unroll
;             for (int m = 0; m < 4; ++m) {
;                 const int row = row0 + ai * 128 + m * 16; float ss = 0.f;
; #pragma unroll
;                 for (int bj = 0; bj < 2; ++bj) {
;                     const size_t off = (size_t)row * DM + col0 + bj * 128;
;                     const f32x4 x0 = xo[m][bj][0] + bperm_f4(src4, acc[ai][bj][m][0]), x1 = xo[m][bj][1] + bperm_f4(src4, acc[ai][bj][m][1]);
;                     *(GAS f32x4*)(out + off) = x0; *(GAS f32x4*)(out + off + 4) = x1;
;                     if (XN) { u32x4 w; w.x = pk2(x0.x, x0.y); w.y = pk2(x0.z, x0.w); w.z = pk2(x1.x, x1.y); w.w = pk2(x1.z, x1.w); *(GAS u32x4*)(XN + off) = w;
;                         ss += (x0.x * x0.x + x0.y * x0.y) + (x0.z * x0.z + x0.w * x0.w) + (x1.x * x1.x + x1.y * x1.y) + (x1.z * x1.z + x1.w * x1.w); }
;                 }
;                 if (XN) { ss += __shfl_xor(ss, 1); ss += __shfl_xor(ss, 2); if ((fr & 3) == 0) ((GAS float*)RS)[(size_t)row * 32 + u.pn * 4 + wc] = ss; }
.LBB0_1185:
	v_lshl_add_u32 v208, s45, 8, v234
	v_lshl_or_b32 v204, s44, 8, v235
	v_ashrrev_i32_e32 v205, 31, v204
	v_ashrrev_i32_e32 v209, 31, v208
	v_lshl_add_u64 v[206:207], v[204:205], 2, s[6:7]
	v_lshlrev_b64 v[122:123], 13, v[208:209]
	v_or_b32_e32 v214, 16, v208
	v_lshl_add_u64 v[122:123], v[206:207], 0, v[122:123]
	v_ashrrev_i32_e32 v215, 31, v214
	global_load_dwordx4 v[190:193], v[122:123], off offset:16 nt
	global_load_dwordx4 v[238:241], v[122:123], off nt
	global_load_dwordx4 v[178:181], v[122:123], off offset:528 nt
	global_load_dwordx4 v[182:185], v[122:123], off offset:512 nt
	v_lshlrev_b64 v[122:123], 13, v[214:215]
	v_or_b32_e32 v212, 32, v208
	v_lshl_add_u64 v[122:123], v[206:207], 0, v[122:123]
	v_ashrrev_i32_e32 v213, 31, v212
	global_load_dwordx4 v[170:173], v[122:123], off offset:16 nt
	global_load_dwordx4 v[174:177], v[122:123], off nt
	global_load_dwordx4 v[162:165], v[122:123], off offset:528 nt
	global_load_dwordx4 v[166:169], v[122:123], off offset:512 nt
	v_lshlrev_b64 v[122:123], 13, v[212:213]
	v_or_b32_e32 v210, 48, v208
	v_lshl_add_u64 v[122:123], v[206:207], 0, v[122:123]
	v_ashrrev_i32_e32 v211, 31, v210
	global_load_dwordx4 v[154:157], v[122:123], off offset:16 nt
	global_load_dwordx4 v[158:161], v[122:123], off nt
	global_load_dwordx4 v[146:149], v[122:123], off offset:528 nt
	global_load_dwordx4 v[150:153], v[122:123], off offset:512 nt
	v_lshlrev_b64 v[122:123], 13, v[210:211]
	v_lshl_add_u64 v[126:127], v[206:207], 0, v[122:123]
	global_load_dwordx4 v[138:141], v[126:127], off offset:16 nt
	global_load_dwordx4 v[142:145], v[126:127], off nt
	global_load_dwordx4 v[122:125], v[126:127], off offset:528 nt
	s_nop 0
	global_load_dwordx4 v[126:129], v[126:127], off offset:512 nt
	ds_bpermute_b32 v130, v233, v130
	ds_bpermute_b32 v131, v233, v131
	ds_bpermute_b32 v134, v233, v134
	ds_bpermute_b32 v135, v233, v135
	ds_bpermute_b32 v136, v233, v136
	ds_bpermute_b32 v137, v233, v137
	ds_bpermute_b32 v132, v233, v132
	ds_bpermute_b32 v133, v233, v133
	v_readlane_b32 s26, v254, 1
	v_lshlrev_b64 v[216:217], 11, v[208:209]
	v_readlane_b32 s27, v254, 2
	v_lshl_add_u64 v[216:217], v[216:217], 0, v[204:205]
	s_waitcnt vmcnt(0) lgkmcnt(0)
	v_pk_add_f32 v[130:131], v[190:191], v[130:131]
	v_cndmask_b32_e64 v190, 0, 1, s[26:27]
	v_pk_add_f32 v[136:137], v[240:241], v[136:137]
	v_pk_add_f32 v[134:135], v[238:239], v[134:135]
	v_pk_add_f32 v[132:133], v[192:193], v[132:133]
	v_lshl_add_u64 v[218:219], v[216:217], 2, s[8:9]
	v_cmp_ne_u32_e64 s[4:5], 1, v190
	s_andn2_b64 vcc, exec, s[26:27]
	v_mov_b32_e32 v237, 0
	global_store_dwordx4 v[218:219], v[134:137], off
	global_store_dwordx4 v[218:219], v[130:133], off offset:16
	s_cbranch_vccnz .LBB0_1187
	v_cvt_pk_bf16_f32 v190, v134, v135
	v_cvt_pk_bf16_f32 v191, v136, v137
	v_lshl_add_u64 v[238:239], v[216:217], 1, s[12:13]
	v_pk_mul_f32 v[136:137], v[136:137], v[136:137]
	v_pk_mul_f32 v[134:135], v[134:135], v[134:135]
	v_cvt_pk_bf16_f32 v192, v130, v131
	v_cvt_pk_bf16_f32 v193, v132, v133
	global_store_dwordx4 v[238:239], v[190:193], off
	v_pk_mul_f32 v[132:133], v[132:133], v[132:133]
	v_pk_mul_f32 v[130:131], v[130:131], v[130:131]
	v_pk_mov_b32 v[190:191], v[134:135], v[136:137] op_sel:[1,0]
	v_mov_b32_e32 v135, v137
	v_pk_add_f32 v[134:135], v[190:191], v[134:135]
	v_mov_b32_e32 v136, v132
	v_mov_b32_e32 v137, v130
	v_mov_b32_e32 v130, v133
	v_pk_add_f32 v[130:131], v[136:137], v[130:131]
	v_add_f32_e32 v132, v134, v135
	v_add_f32_e32 v131, v132, v131
	v_add_f32_e32 v237, v130, v131

; #define GAS __attribute__((address_space(1)))
; __device__ __forceinline__ unsigned pk2(float lo, float hi) { unsigned r; asm("v_cvt_pk_bf16_f32 %0, %1, %2" : "=v"(r) : "v"(lo), "v"(hi)); return r; }
; __device__ __forceinline__ f32x4 bperm_f4(int src4, f32x4 v) { return (f32x4){bperm_f(src4, v.x), bperm_f(src4, v.y), bperm_f(src4, v.z), bperm_f(src4, v.w)}; }
;     __device__ __forceinline__ void operator()(const pg8::f32x4 (&acc)[2][2][4][2], const pg8::Unit& u, int wr, int wc, int fr, int fq) const {
;     ...
;             for (int m = 0; m < 4; ++m)
; #pragma unroll
;                 for (int bj = 0; bj < 2; ++bj) { const size_t off = (size_t)(row0 + ai * 128 + m * 16) * DM + col0 + bj * 128; xo[m][bj][0] = *(const GAS f32x4*)(xold + off); xo[m][bj][1] = *(const GAS f32x4*)(xold + off + 4); }
;             __builtin_amdgcn_sched_barrier(0);
; #pragma unroll
;             for (int m = 0; m < 4; ++m) {
;                 const int row = row0 + ai * 128 + m * 16; float ss = 0.f;
; #pragma unroll
;                 for (int bj = 0; bj < 2; ++bj) {
;                     const size_t off = (size_t)row * DM + col0 + bj * 128;
;                     const f32x4 x0 = xo[m][bj][0] + bperm_f4(src4, acc[ai][bj][m][0]), x1 = xo[m][bj][1] + bperm_f4(src4, acc[ai][bj][m][1]);
;                     *(GAS f32x4*)(out + off) = x0; *(GAS f32x4*)(out + off + 4) = x1;
;                     if (XN) { u32x4 w; w.x = pk2(x0.x, x0.y); w.y = pk2(x0.z, x0.w); w.z = pk2(x1.x, x1.y); w.w = pk2(x1.z, x1.w); *(GAS u32x4*)(XN + off) = w;
;                         ss += (x0.x * x0.x + x0.y * x0.y) + (x0.z * x0.z + x0.w * x0.w) + (x1.x * x1.x + x1.y * x1.y) + (x1.z * x1.z + x1.w * x1.w); }
;                 }
;                 if (XN) { ss += __shfl_xor(ss, 1); ss += __shfl_xor(ss, 2); if ((fr & 3) == 0) ((GAS float*)RS)[(size_t)row * 32 + u.pn * 4 + wc] = ss; }
.LBB0_1209:
	v_add_u32_e32 v128, 0x80, v208
	v_ashrrev_i32_e32 v129, 31, v128
	s_waitcnt lgkmcnt(0)
	v_lshlrev_b64 v[66:67], 13, v[128:129]
	v_add_u32_e32 v126, 0x90, v208
	v_lshl_add_u64 v[66:67], v[206:207], 0, v[66:67]
	v_ashrrev_i32_e32 v127, 31, v126
	global_load_dwordx4 v[132:135], v[66:67], off offset:16 nt
	global_load_dwordx4 v[136:139], v[66:67], off nt
	global_load_dwordx4 v[114:117], v[66:67], off offset:528 nt
	global_load_dwordx4 v[118:121], v[66:67], off offset:512 nt
	v_lshlrev_b64 v[66:67], 13, v[126:127]
	v_add_u32_e32 v124, 0xa0, v208
	v_lshl_add_u64 v[66:67], v[206:207], 0, v[66:67]
	v_ashrrev_i32_e32 v125, 31, v124
	global_load_dwordx4 v[106:109], v[66:67], off offset:16 nt
	global_load_dwordx4 v[110:113], v[66:67], off nt
	global_load_dwordx4 v[98:101], v[66:67], off offset:528 nt
	global_load_dwordx4 v[102:105], v[66:67], off offset:512 nt
	v_lshlrev_b64 v[66:67], 13, v[124:125]
	v_add_u32_e32 v122, 0xb0, v208
	v_lshl_add_u64 v[66:67], v[206:207], 0, v[66:67]
	v_ashrrev_i32_e32 v123, 31, v122
	global_load_dwordx4 v[90:93], v[66:67], off offset:16 nt
	global_load_dwordx4 v[94:97], v[66:67], off nt
	global_load_dwordx4 v[82:85], v[66:67], off offset:528 nt
	global_load_dwordx4 v[86:89], v[66:67], off offset:512 nt
	v_lshlrev_b64 v[66:67], 13, v[122:123]
	v_lshl_add_u64 v[70:71], v[206:207], 0, v[66:67]
	global_load_dwordx4 v[74:77], v[70:71], off offset:16 nt
	global_load_dwordx4 v[78:81], v[70:71], off nt
	global_load_dwordx4 v[66:69], v[70:71], off offset:528 nt
	s_nop 0
	global_load_dwordx4 v[70:73], v[70:71], off offset:512 nt
	ds_bpermute_b32 v62, v233, v62
	ds_bpermute_b32 v63, v233, v63
	ds_bpermute_b32 v64, v233, v64
	ds_bpermute_b32 v65, v233, v65
	ds_bpermute_b32 v58, v233, v58
	ds_bpermute_b32 v59, v233, v59
	ds_bpermute_b32 v60, v233, v60
	ds_bpermute_b32 v61, v233, v61
	v_lshlrev_b64 v[130:131], 11, v[128:129]
	v_lshl_add_u64 v[130:131], v[130:131], 0, v[204:205]
	s_waitcnt vmcnt(14) lgkmcnt(6)
	v_pk_add_f32 v[62:63], v[136:137], v[62:63]
	s_waitcnt lgkmcnt(4)
	v_pk_add_f32 v[64:65], v[138:139], v[64:65]
	s_waitcnt lgkmcnt(2)
	v_pk_add_f32 v[58:59], v[132:133], v[58:59]
	s_waitcnt lgkmcnt(0)
	v_pk_add_f32 v[60:61], v[134:135], v[60:61]
	v_lshl_add_u64 v[132:133], v[130:131], 2, s[8:9]
	s_and_b64 vcc, exec, s[4:5]
	v_mov_b32_e32 v134, 0
	global_store_dwordx4 v[132:133], v[62:65], off
	global_store_dwordx4 v[132:133], v[58:61], off offset:16
	s_cbranch_vccnz .LBB0_1211
	v_cvt_pk_bf16_f32 v134, v62, v63
	v_cvt_pk_bf16_f32 v135, v64, v65
	v_lshl_add_u64 v[138:139], v[130:131], 1, s[12:13]
	v_pk_mul_f32 v[64:65], v[64:65], v[64:65]
	v_pk_mul_f32 v[62:63], v[62:63], v[62:63]
	v_cvt_pk_bf16_f32 v136, v58, v59
	v_cvt_pk_bf16_f32 v137, v60, v61
	global_store_dwordx4 v[138:139], v[134:137], off
	v_pk_mul_f32 v[60:61], v[60:61], v[60:61]
	v_pk_mul_f32 v[58:59], v[58:59], v[58:59]
	v_pk_mov_b32 v[134:135], v[62:63], v[64:65] op_sel:[1,0]
	v_mov_b32_e32 v63, v65
	v_pk_add_f32 v[62:63], v[134:135], v[62:63]
	v_mov_b32_e32 v64, v60
	v_mov_b32_e32 v65, v58
	v_mov_b32_e32 v58, v61
	v_pk_add_f32 v[58:59], v[64:65], v[58:59]
	v_add_f32_e32 v60, v62, v63
	v_add_f32_e32 v59, v60, v59
	v_add_f32_e32 v134, v58, v59
